# hand-written SSD chunk-state chains (decay vectors of all steps by LDS-DMA, operand register ring 4 steps deep, no per-step round trip); GLU epilogue and S5 local scan code shrunk
# speedup vs baseline: 1.3028x; 1.0021x over previous
.Ls5l_rows1:
	s_mul_i32 s100, s100, 0x2440
	s_lshl_b32 s101, s99, 6
	s_add_u32 s100, s100, s101
	s_add_u32 s100, s100, 0x3a26040
	s_add_u32 s44, s96, s100
	s_addc_u32 s45, s97, 0
	s_lshl_b32 s101, s36, 1
	s_add_u32 s101, s101, s55
	s_lshl_b32 s101, s101, 4
	s_add_u32 s101, s101, s99
	s_lshl_b32 s100, s101, 12
	s_add_u32 s100, s100, 0xd1c4000
	s_add_u32 s46, s96, s100
	s_addc_u32 s47, s97, 0
	s_lshl_b32 s100, s101, 11
	s_add_u32 s100, s100, 0xd1a4000
	s_add_u32 s48, s96, s100
	s_addc_u32 s49, s97, 0
	s_lshl_b32 s100, s98, 4
	s_add_u32 s100, s100, s99
	s_lshl_b32 s100, s100, 1
	s_add_u32 s100, s100, s55
	s_lshl_b32 s100, s100, 9
	s_add_u32 s100, s100, 0xcba4000
	s_add_u32 s56, s96, s100
	s_addc_u32 s57, s97, 0
	v_mul_lo_u32 v11, v4, s52
	v_lshl_add_u32 v11, v5, 5, v11
	v_add_u32_e32 v12, s53, v11
	v_mov_b32_e32 v70, 0
	v_mov_b32_e32 v71, 0
	v_mov_b32_e32 v72, 0
	v_mov_b32_e32 v73, 0
	v_mov_b32_e32 v74, 0
	v_mov_b32_e32 v75, 0
	v_mov_b32_e32 v76, 0
	v_mov_b32_e32 v77, 0
	v_mov_b32_e32 v78, 0
	v_mov_b32_e32 v79, 0
	v_mov_b32_e32 v80, 0
	v_mov_b32_e32 v81, 0
	v_mov_b32_e32 v82, 0
	v_mov_b32_e32 v83, 0
	v_mov_b32_e32 v84, 0
	v_mov_b32_e32 v85, 0
	s_mov_b64 s[38:39], exec
	s_mov_b32 exec_lo, -1
	s_mov_b32 exec_hi, 0
	global_load_dwordx4 v[70:73], v11, s[44:45]
	global_load_dwordx4 v[74:77], v11, s[44:45] offset:16
	global_load_dwordx4 v[78:81], v12, s[44:45]
	global_load_dwordx4 v[82:85], v12, s[44:45] offset:16
	s_mov_b64 exec, s[38:39]
	global_load_dwordx4 v[86:89], v8, s[46:47]
	global_load_dwordx4 v[90:93], v8, s[46:47] offset:512
	global_load_dwordx4 v[94:97], v8, s[46:47] offset:1024
	global_load_dwordx4 v[98:101], v8, s[46:47] offset:1536
	global_load_dwordx4 v[102:105], v8, s[46:47] offset:2048
	global_load_dwordx4 v[106:109], v8, s[46:47] offset:2560
	global_load_dwordx4 v[110:113], v8, s[46:47] offset:3072
	global_load_dwordx4 v[114:117], v8, s[46:47] offset:3584
	global_load_dwordx2 v[118:119], v9, s[48:49]
	s_waitcnt vmcnt(13)
	v_cvt_pk_bf16_f32 v120, v20, v21
	v_cvt_pk_bf16_f32 v121, v22, v23
	v_cvt_pk_bf16_f32 v122, v24, v25
	v_cvt_pk_bf16_f32 v123, v26, v27
	v_cvt_pk_bf16_f32 v124, v28, v29
	v_cvt_pk_bf16_f32 v125, v30, v31
	v_cvt_pk_bf16_f32 v126, v32, v33
	v_cvt_pk_bf16_f32 v127, v34, v35
	s_nop 1
	v_mfma_f32_16x16x32_bf16 v[128:131], v[120:123], v[36:39], 0
	v_mfma_f32_16x16x32_bf16 v[132:135], v[124:127], v[36:39], 0
	v_mfma_f32_16x16x32_bf16 v[136:139], v[120:123], v[40:43], 0
	v_mfma_f32_16x16x32_bf16 v[140:143], v[124:127], v[40:43], 0
	v_mfma_f32_16x16x32_bf16 v[144:147], v[120:123], v[44:47], 0
	v_mfma_f32_16x16x32_bf16 v[148:151], v[124:127], v[44:47], 0
	v_mfma_f32_16x16x32_bf16 v[152:155], v[120:123], v[48:51], 0
	v_mfma_f32_16x16x32_bf16 v[156:159], v[124:127], v[48:51], 0
	v_mfma_f32_16x16x32_bf16 v[160:163], v[120:123], v[52:55], 0
	v_mfma_f32_16x16x32_bf16 v[164:167], v[124:127], v[52:55], 0
	v_mfma_f32_16x16x32_bf16 v[168:171], v[120:123], v[56:59], 0
	v_mfma_f32_16x16x32_bf16 v[172:175], v[124:127], v[56:59], 0
	v_mfma_f32_16x16x32_bf16 v[176:179], v[120:123], v[60:63], 0
	v_mfma_f32_16x16x32_bf16 v[180:183], v[124:127], v[60:63], 0
	v_mfma_f32_16x16x32_bf16 v[184:187], v[120:123], v[64:67], 0
	v_mfma_f32_16x16x32_bf16 v[188:191], v[124:127], v[64:67], 0
	ds_write_b32 v6, v128 offset:0
	ds_write_b32 v6, v129 offset:528
	ds_write_b32 v6, v130 offset:1056
	ds_write_b32 v6, v131 offset:1584
	ds_write_b32 v6, v132 offset:8448
	ds_write_b32 v6, v133 offset:8976
	ds_write_b32 v6, v134 offset:9504
	ds_write_b32 v6, v135 offset:10032
	ds_write_b32 v6, v136 offset:64
	ds_write_b32 v6, v137 offset:592
	ds_write_b32 v6, v138 offset:1120
	ds_write_b32 v6, v139 offset:1648
	ds_write_b32 v6, v140 offset:8512
	ds_write_b32 v6, v141 offset:9040
	ds_write_b32 v6, v142 offset:9568
	ds_write_b32 v6, v143 offset:10096
	ds_write_b32 v6, v144 offset:128
	ds_write_b32 v6, v145 offset:656
	ds_write_b32 v6, v146 offset:1184
	ds_write_b32 v6, v147 offset:1712
	ds_write_b32 v6, v148 offset:8576
	ds_write_b32 v6, v149 offset:9104
	ds_write_b32 v6, v150 offset:9632
	ds_write_b32 v6, v151 offset:10160
	ds_write_b32 v6, v152 offset:192
	ds_write_b32 v6, v153 offset:720
	ds_write_b32 v6, v154 offset:1248
	ds_write_b32 v6, v155 offset:1776
	ds_write_b32 v6, v156 offset:8640
	ds_write_b32 v6, v157 offset:9168
	ds_write_b32 v6, v158 offset:9696
	ds_write_b32 v6, v159 offset:10224
	ds_write_b32 v6, v160 offset:256
	ds_write_b32 v6, v161 offset:784
	ds_write_b32 v6, v162 offset:1312
	ds_write_b32 v6, v163 offset:1840
	ds_write_b32 v6, v164 offset:8704
	ds_write_b32 v6, v165 offset:9232
	ds_write_b32 v6, v166 offset:9760
	ds_write_b32 v6, v167 offset:10288
	ds_write_b32 v6, v168 offset:320
	ds_write_b32 v6, v169 offset:848
	ds_write_b32 v6, v170 offset:1376
	ds_write_b32 v6, v171 offset:1904
	ds_write_b32 v6, v172 offset:8768
	ds_write_b32 v6, v173 offset:9296
	ds_write_b32 v6, v174 offset:9824
	ds_write_b32 v6, v175 offset:10352
	ds_write_b32 v6, v176 offset:384
	ds_write_b32 v6, v177 offset:912
	ds_write_b32 v6, v178 offset:1440
	ds_write_b32 v6, v179 offset:1968
	ds_write_b32 v6, v180 offset:8832
	ds_write_b32 v6, v181 offset:9360
	ds_write_b32 v6, v182 offset:9888
	ds_write_b32 v6, v183 offset:10416
	ds_write_b32 v6, v184 offset:448
	ds_write_b32 v6, v185 offset:976
	ds_write_b32 v6, v186 offset:1504
	ds_write_b32 v6, v187 offset:2032
	s_nop 4
	ds_write_b32 v6, v188 offset:8896
	ds_write_b32 v6, v189 offset:9424
	ds_write_b32 v6, v190 offset:9952
	ds_write_b32 v6, v191 offset:10480
	v_mov_b32_e32 v192, 0
	v_mov_b32_e32 v193, 0
	s_waitcnt lgkmcnt(0)
	s_cmp_eq_u32 s54, 0
	s_cselect_b32 s100, 0, 16368
	s_mov_b32 s101, 0xfffffdf0
	s_cselect_b32 s101, 528, s101
	v_add_u32_e32 v13, s100, v7
	ds_read_b64 v[128:129], v13
	v_add_u32_e32 v13, s101, v13
	ds_read_b64 v[130:131], v13
	v_add_u32_e32 v13, s101, v13
	ds_read_b64 v[132:133], v13
	v_add_u32_e32 v13, s101, v13
	ds_read_b64 v[134:135], v13
	v_add_u32_e32 v13, s101, v13
	ds_read_b64 v[136:137], v13
	v_add_u32_e32 v13, s101, v13
	ds_read_b64 v[138:139], v13
	v_add_u32_e32 v13, s101, v13
	ds_read_b64 v[140:141], v13
	v_add_u32_e32 v13, s101, v13
	ds_read_b64 v[142:143], v13
	v_add_u32_e32 v13, s101, v13
	ds_read_b64 v[144:145], v13
	v_add_u32_e32 v13, s101, v13
	ds_read_b64 v[146:147], v13
	v_add_u32_e32 v13, s101, v13
	ds_read_b64 v[148:149], v13
	v_add_u32_e32 v13, s101, v13
	ds_read_b64 v[150:151], v13
	v_add_u32_e32 v13, s101, v13
	ds_read_b64 v[152:153], v13
	v_add_u32_e32 v13, s101, v13
	ds_read_b64 v[154:155], v13
	v_add_u32_e32 v13, s101, v13
	ds_read_b64 v[156:157], v13
	v_add_u32_e32 v13, s101, v13
	ds_read_b64 v[158:159], v13
	v_add_u32_e32 v13, s101, v13
	s_waitcnt lgkmcnt(15)
	v_mul_f32_e32 v194, v69, v193
	v_mul_f32_e32 v195, v69, v192
	v_fma_f32 v0, v68, v192, -v194
	v_fma_f32 v1, v68, v193, v195
	v_add_f32_e32 v192, v0, v128
	v_add_f32_e32 v193, v1, v129
	s_waitcnt lgkmcnt(14)
	v_mul_f32_e32 v194, v69, v193
	v_mul_f32_e32 v195, v69, v192
	v_fma_f32 v0, v68, v192, -v194
	v_fma_f32 v1, v68, v193, v195
	v_add_f32_e32 v192, v0, v130
	v_add_f32_e32 v193, v1, v131
	s_waitcnt lgkmcnt(13)
	v_mul_f32_e32 v194, v69, v193
	v_mul_f32_e32 v195, v69, v192
	v_fma_f32 v0, v68, v192, -v194
	v_fma_f32 v1, v68, v193, v195
	v_add_f32_e32 v192, v0, v132
	v_add_f32_e32 v193, v1, v133
	s_waitcnt lgkmcnt(12)
	v_mul_f32_e32 v194, v69, v193
	v_mul_f32_e32 v195, v69, v192
	v_fma_f32 v0, v68, v192, -v194
	v_fma_f32 v1, v68, v193, v195
	v_add_f32_e32 v192, v0, v134
	v_add_f32_e32 v193, v1, v135
	s_waitcnt lgkmcnt(11)
	v_mul_f32_e32 v194, v69, v193
	v_mul_f32_e32 v195, v69, v192
	v_fma_f32 v0, v68, v192, -v194
	v_fma_f32 v1, v68, v193, v195
	v_add_f32_e32 v192, v0, v136
	v_add_f32_e32 v193, v1, v137
	s_waitcnt lgkmcnt(10)
	v_mul_f32_e32 v194, v69, v193
	v_mul_f32_e32 v195, v69, v192
	v_fma_f32 v0, v68, v192, -v194
	v_fma_f32 v1, v68, v193, v195
	v_add_f32_e32 v192, v0, v138
	v_add_f32_e32 v193, v1, v139
	s_waitcnt lgkmcnt(9)
	v_mul_f32_e32 v194, v69, v193
	v_mul_f32_e32 v195, v69, v192
	v_fma_f32 v0, v68, v192, -v194
	v_fma_f32 v1, v68, v193, v195
	v_add_f32_e32 v192, v0, v140
	v_add_f32_e32 v193, v1, v141
	s_waitcnt lgkmcnt(8)
	v_mul_f32_e32 v194, v69, v193
	v_mul_f32_e32 v195, v69, v192
	v_fma_f32 v0, v68, v192, -v194
	v_fma_f32 v1, v68, v193, v195
	v_add_f32_e32 v192, v0, v142
	v_add_f32_e32 v193, v1, v143
	ds_read_b64 v[128:129], v13
	v_add_u32_e32 v13, s101, v13
	ds_read_b64 v[130:131], v13
	v_add_u32_e32 v13, s101, v13
	ds_read_b64 v[132:133], v13
	v_add_u32_e32 v13, s101, v13
	ds_read_b64 v[134:135], v13
	v_add_u32_e32 v13, s101, v13
	ds_read_b64 v[136:137], v13
	v_add_u32_e32 v13, s101, v13
	ds_read_b64 v[138:139], v13
	v_add_u32_e32 v13, s101, v13
	ds_read_b64 v[140:141], v13
	v_add_u32_e32 v13, s101, v13
	ds_read_b64 v[142:143], v13
	v_add_u32_e32 v13, s101, v13
	s_waitcnt lgkmcnt(15)
	v_mul_f32_e32 v194, v69, v193
	v_mul_f32_e32 v195, v69, v192
	v_fma_f32 v0, v68, v192, -v194
	v_fma_f32 v1, v68, v193, v195
	v_add_f32_e32 v192, v0, v144
	v_add_f32_e32 v193, v1, v145
	s_waitcnt lgkmcnt(14)
	v_mul_f32_e32 v194, v69, v193
	v_mul_f32_e32 v195, v69, v192
	v_fma_f32 v0, v68, v192, -v194
	v_fma_f32 v1, v68, v193, v195
	v_add_f32_e32 v192, v0, v146
	v_add_f32_e32 v193, v1, v147
	s_waitcnt lgkmcnt(13)
	v_mul_f32_e32 v194, v69, v193
	v_mul_f32_e32 v195, v69, v192
	v_fma_f32 v0, v68, v192, -v194
	v_fma_f32 v1, v68, v193, v195
	v_add_f32_e32 v192, v0, v148
	v_add_f32_e32 v193, v1, v149
	s_waitcnt lgkmcnt(12)
	v_mul_f32_e32 v194, v69, v193
	v_mul_f32_e32 v195, v69, v192
	v_fma_f32 v0, v68, v192, -v194
	v_fma_f32 v1, v68, v193, v195
	v_add_f32_e32 v192, v0, v150
	v_add_f32_e32 v193, v1, v151
	s_waitcnt lgkmcnt(11)
	v_mul_f32_e32 v194, v69, v193
	v_mul_f32_e32 v195, v69, v192
	v_fma_f32 v0, v68, v192, -v194
	v_fma_f32 v1, v68, v193, v195
	v_add_f32_e32 v192, v0, v152
	v_add_f32_e32 v193, v1, v153
	s_waitcnt lgkmcnt(10)
	v_mul_f32_e32 v194, v69, v193
	v_mul_f32_e32 v195, v69, v192
	v_fma_f32 v0, v68, v192, -v194
	v_fma_f32 v1, v68, v193, v195
	v_add_f32_e32 v192, v0, v154
	v_add_f32_e32 v193, v1, v155
	s_waitcnt lgkmcnt(9)
	v_mul_f32_e32 v194, v69, v193
	v_mul_f32_e32 v195, v69, v192
	v_fma_f32 v0, v68, v192, -v194
	v_fma_f32 v1, v68, v193, v195
	v_add_f32_e32 v192, v0, v156
	v_add_f32_e32 v193, v1, v157
	s_waitcnt lgkmcnt(8)
	v_mul_f32_e32 v194, v69, v193
	v_mul_f32_e32 v195, v69, v192
	v_fma_f32 v0, v68, v192, -v194
	v_fma_f32 v1, v68, v193, v195
	v_add_f32_e32 v192, v0, v158
	v_add_f32_e32 v193, v1, v159
	ds_read_b64 v[144:145], v13
	v_add_u32_e32 v13, s101, v13
	ds_read_b64 v[146:147], v13
	v_add_u32_e32 v13, s101, v13
	ds_read_b64 v[148:149], v13
	v_add_u32_e32 v13, s101, v13
	ds_read_b64 v[150:151], v13
	v_add_u32_e32 v13, s101, v13
	ds_read_b64 v[152:153], v13
	v_add_u32_e32 v13, s101, v13
	ds_read_b64 v[154:155], v13
	v_add_u32_e32 v13, s101, v13
	ds_read_b64 v[156:157], v13
	v_add_u32_e32 v13, s101, v13
	ds_read_b64 v[158:159], v13
	v_add_u32_e32 v13, s101, v13
	s_waitcnt lgkmcnt(15)
	v_mul_f32_e32 v194, v69, v193
	v_mul_f32_e32 v195, v69, v192
	v_fma_f32 v0, v68, v192, -v194
	v_fma_f32 v1, v68, v193, v195
	v_add_f32_e32 v192, v0, v128
	v_add_f32_e32 v193, v1, v129
	s_waitcnt lgkmcnt(14)
	v_mul_f32_e32 v194, v69, v193
	v_mul_f32_e32 v195, v69, v192
	v_fma_f32 v0, v68, v192, -v194
	v_fma_f32 v1, v68, v193, v195
	v_add_f32_e32 v192, v0, v130
	v_add_f32_e32 v193, v1, v131
	s_waitcnt lgkmcnt(13)
	v_mul_f32_e32 v194, v69, v193
	v_mul_f32_e32 v195, v69, v192
	v_fma_f32 v0, v68, v192, -v194
	v_fma_f32 v1, v68, v193, v195
	v_add_f32_e32 v192, v0, v132
	v_add_f32_e32 v193, v1, v133
	s_waitcnt lgkmcnt(12)
	v_mul_f32_e32 v194, v69, v193
	v_mul_f32_e32 v195, v69, v192
	v_fma_f32 v0, v68, v192, -v194
	v_fma_f32 v1, v68, v193, v195
	v_add_f32_e32 v192, v0, v134
	v_add_f32_e32 v193, v1, v135
	s_waitcnt lgkmcnt(11)
	v_mul_f32_e32 v194, v69, v193
	v_mul_f32_e32 v195, v69, v192
	v_fma_f32 v0, v68, v192, -v194
	v_fma_f32 v1, v68, v193, v195
	v_add_f32_e32 v192, v0, v136
	v_add_f32_e32 v193, v1, v137
	s_waitcnt lgkmcnt(10)
	v_mul_f32_e32 v194, v69, v193
	v_mul_f32_e32 v195, v69, v192
	v_fma_f32 v0, v68, v192, -v194
	v_fma_f32 v1, v68, v193, v195
	v_add_f32_e32 v192, v0, v138
	v_add_f32_e32 v193, v1, v139
	s_waitcnt lgkmcnt(9)
	v_mul_f32_e32 v194, v69, v193
	v_mul_f32_e32 v195, v69, v192
	v_fma_f32 v0, v68, v192, -v194
	v_fma_f32 v1, v68, v193, v195
	v_add_f32_e32 v192, v0, v140
	v_add_f32_e32 v193, v1, v141
	s_waitcnt lgkmcnt(8)
	v_mul_f32_e32 v194, v69, v193
	v_mul_f32_e32 v195, v69, v192
	v_fma_f32 v0, v68, v192, -v194
	v_fma_f32 v1, v68, v193, v195
	v_add_f32_e32 v192, v0, v142
	v_add_f32_e32 v193, v1, v143
	s_waitcnt lgkmcnt(7)
	v_mul_f32_e32 v194, v69, v193
	v_mul_f32_e32 v195, v69, v192
	v_fma_f32 v0, v68, v192, -v194
	v_fma_f32 v1, v68, v193, v195
	v_add_f32_e32 v192, v0, v144
	v_add_f32_e32 v193, v1, v145
	s_waitcnt lgkmcnt(6)
	v_mul_f32_e32 v194, v69, v193
	v_mul_f32_e32 v195, v69, v192
	v_fma_f32 v0, v68, v192, -v194
	v_fma_f32 v1, v68, v193, v195
	v_add_f32_e32 v192, v0, v146
	v_add_f32_e32 v193, v1, v147
	s_waitcnt lgkmcnt(5)
	v_mul_f32_e32 v194, v69, v193
	v_mul_f32_e32 v195, v69, v192
	v_fma_f32 v0, v68, v192, -v194
	v_fma_f32 v1, v68, v193, v195
	v_add_f32_e32 v192, v0, v148
	v_add_f32_e32 v193, v1, v149
	s_waitcnt lgkmcnt(4)
	v_mul_f32_e32 v194, v69, v193
	v_mul_f32_e32 v195, v69, v192
	v_fma_f32 v0, v68, v192, -v194
	v_fma_f32 v1, v68, v193, v195
	v_add_f32_e32 v192, v0, v150
	v_add_f32_e32 v193, v1, v151
	s_waitcnt lgkmcnt(3)
	v_mul_f32_e32 v194, v69, v193
	v_mul_f32_e32 v195, v69, v192
	v_fma_f32 v0, v68, v192, -v194
	v_fma_f32 v1, v68, v193, v195
	v_add_f32_e32 v192, v0, v152
	v_add_f32_e32 v193, v1, v153
	s_waitcnt lgkmcnt(2)
	v_mul_f32_e32 v194, v69, v193
	v_mul_f32_e32 v195, v69, v192
	v_fma_f32 v0, v68, v192, -v194
	v_fma_f32 v1, v68, v193, v195
	v_add_f32_e32 v192, v0, v154
	v_add_f32_e32 v193, v1, v155
	s_waitcnt lgkmcnt(1)
	v_mul_f32_e32 v194, v69, v193
	v_mul_f32_e32 v195, v69, v192
	v_fma_f32 v0, v68, v192, -v194
	v_fma_f32 v1, v68, v193, v195
	v_add_f32_e32 v192, v0, v156
	v_add_f32_e32 v193, v1, v157
	s_waitcnt lgkmcnt(0)
	v_mul_f32_e32 v194, v69, v193
	v_mul_f32_e32 v195, v69, v192
	v_fma_f32 v0, v68, v192, -v194
	v_fma_f32 v1, v68, v193, v195
	v_add_f32_e32 v192, v0, v158
	v_add_f32_e32 v193, v1, v159
	global_store_dwordx2 v10, v[192:193], s[50:51]
	s_nop 1
	s_add_u32 s43, s41, 4096
	s_lshr_b32 s98, s43, 5
	s_bfe_u32 s99, s43, 0x40001
	s_and_b32 s54, s43, 1
	s_cmpk_lt_u32 s98, 0x80
	s_cbranch_scc1 .Ls5l_ctx2
	s_sub_u32 s100, s98, 0x80
	s_lshr_b32 s101, s100, 5
	s_and_b32 s100, s100, 31
	s_lshl_b32 s101, s101, 10
	s_lshl_b32 s100, s100, 1
	s_add_u32 s100, s100, s101
	s_add_u32 s100, s100, 0x1000
	s_mov_b32 s52, 0x91000
	s_movk_i32 s53, 0x2440
	s_branch .Ls5l_rows2

.Ls5l_rows2:
	s_mul_i32 s100, s100, 0x2440
	s_lshl_b32 s101, s99, 6
	s_add_u32 s100, s100, s101
	s_add_u32 s100, s100, 0x3a26040
	s_add_u32 s44, s96, s100
	s_addc_u32 s45, s97, 0
	s_lshl_b32 s101, s36, 1
	s_add_u32 s101, s101, s54
	s_lshl_b32 s101, s101, 4
	s_add_u32 s101, s101, s99
	s_lshl_b32 s100, s101, 12
	s_add_u32 s100, s100, 0xd1c4000
	s_add_u32 s46, s96, s100
	s_addc_u32 s47, s97, 0
	s_lshl_b32 s100, s101, 11
	s_add_u32 s100, s100, 0xd1a4000
	s_add_u32 s48, s96, s100
	s_addc_u32 s49, s97, 0
	s_lshl_b32 s100, s98, 4
	s_add_u32 s100, s100, s99
	s_lshl_b32 s100, s100, 1
	s_add_u32 s100, s100, s54
	s_lshl_b32 s100, s100, 9
	s_add_u32 s100, s100, 0xcba4000
	s_add_u32 s50, s96, s100
	s_addc_u32 s51, s97, 0
	v_mul_lo_u32 v11, v4, s52
	v_lshl_add_u32 v11, v5, 5, v11
	v_add_u32_e32 v12, s53, v11
	v_mov_b32_e32 v20, 0
	v_mov_b32_e32 v21, 0
	v_mov_b32_e32 v22, 0
	v_mov_b32_e32 v23, 0
	v_mov_b32_e32 v24, 0
	v_mov_b32_e32 v25, 0
	v_mov_b32_e32 v26, 0
	v_mov_b32_e32 v27, 0
	v_mov_b32_e32 v28, 0
	v_mov_b32_e32 v29, 0
	v_mov_b32_e32 v30, 0
	v_mov_b32_e32 v31, 0
	v_mov_b32_e32 v32, 0
	v_mov_b32_e32 v33, 0
	v_mov_b32_e32 v34, 0
	v_mov_b32_e32 v35, 0
	s_mov_b64 s[38:39], exec
	s_mov_b32 exec_lo, -1
	s_mov_b32 exec_hi, 0
	global_load_dwordx4 v[20:23], v11, s[44:45]
	global_load_dwordx4 v[24:27], v11, s[44:45] offset:16
	global_load_dwordx4 v[28:31], v12, s[44:45]
	global_load_dwordx4 v[32:35], v12, s[44:45] offset:16
	s_mov_b64 exec, s[38:39]
	global_load_dwordx4 v[36:39], v8, s[46:47]
	global_load_dwordx4 v[40:43], v8, s[46:47] offset:512
	global_load_dwordx4 v[44:47], v8, s[46:47] offset:1024
	global_load_dwordx4 v[48:51], v8, s[46:47] offset:1536
	global_load_dwordx4 v[52:55], v8, s[46:47] offset:2048
	global_load_dwordx4 v[56:59], v8, s[46:47] offset:2560
	global_load_dwordx4 v[60:63], v8, s[46:47] offset:3072
	global_load_dwordx4 v[64:67], v8, s[46:47] offset:3584
	global_load_dwordx2 v[68:69], v9, s[48:49]
	s_waitcnt vmcnt(14)
	v_cvt_pk_bf16_f32 v120, v70, v71
	v_cvt_pk_bf16_f32 v121, v72, v73
	v_cvt_pk_bf16_f32 v122, v74, v75
	v_cvt_pk_bf16_f32 v123, v76, v77
	v_cvt_pk_bf16_f32 v124, v78, v79
	v_cvt_pk_bf16_f32 v125, v80, v81
	v_cvt_pk_bf16_f32 v126, v82, v83
	v_cvt_pk_bf16_f32 v127, v84, v85
	s_nop 1
	v_mfma_f32_16x16x32_bf16 v[128:131], v[120:123], v[86:89], 0
	v_mfma_f32_16x16x32_bf16 v[132:135], v[124:127], v[86:89], 0
	v_mfma_f32_16x16x32_bf16 v[136:139], v[120:123], v[90:93], 0
	v_mfma_f32_16x16x32_bf16 v[140:143], v[124:127], v[90:93], 0
	v_mfma_f32_16x16x32_bf16 v[144:147], v[120:123], v[94:97], 0
	v_mfma_f32_16x16x32_bf16 v[148:151], v[124:127], v[94:97], 0
	v_mfma_f32_16x16x32_bf16 v[152:155], v[120:123], v[98:101], 0
	v_mfma_f32_16x16x32_bf16 v[156:159], v[124:127], v[98:101], 0
	v_mfma_f32_16x16x32_bf16 v[160:163], v[120:123], v[102:105], 0
	v_mfma_f32_16x16x32_bf16 v[164:167], v[124:127], v[102:105], 0
	v_mfma_f32_16x16x32_bf16 v[168:171], v[120:123], v[106:109], 0
	v_mfma_f32_16x16x32_bf16 v[172:175], v[124:127], v[106:109], 0
	v_mfma_f32_16x16x32_bf16 v[176:179], v[120:123], v[110:113], 0
	v_mfma_f32_16x16x32_bf16 v[180:183], v[124:127], v[110:113], 0
	v_mfma_f32_16x16x32_bf16 v[184:187], v[120:123], v[114:117], 0
	v_mfma_f32_16x16x32_bf16 v[188:191], v[124:127], v[114:117], 0
	ds_write_b32 v6, v128 offset:0
	ds_write_b32 v6, v129 offset:528
	ds_write_b32 v6, v130 offset:1056
	ds_write_b32 v6, v131 offset:1584
	ds_write_b32 v6, v132 offset:8448
	ds_write_b32 v6, v133 offset:8976
	ds_write_b32 v6, v134 offset:9504
	ds_write_b32 v6, v135 offset:10032
	ds_write_b32 v6, v136 offset:64
	ds_write_b32 v6, v137 offset:592
	ds_write_b32 v6, v138 offset:1120
	ds_write_b32 v6, v139 offset:1648
	ds_write_b32 v6, v140 offset:8512
	ds_write_b32 v6, v141 offset:9040
	ds_write_b32 v6, v142 offset:9568
	ds_write_b32 v6, v143 offset:10096
	ds_write_b32 v6, v144 offset:128
	ds_write_b32 v6, v145 offset:656
	ds_write_b32 v6, v146 offset:1184
	ds_write_b32 v6, v147 offset:1712
	ds_write_b32 v6, v148 offset:8576
	ds_write_b32 v6, v149 offset:9104
	ds_write_b32 v6, v150 offset:9632
	ds_write_b32 v6, v151 offset:10160
	ds_write_b32 v6, v152 offset:192
	ds_write_b32 v6, v153 offset:720
	ds_write_b32 v6, v154 offset:1248
	ds_write_b32 v6, v155 offset:1776
	ds_write_b32 v6, v156 offset:8640
	ds_write_b32 v6, v157 offset:9168
	ds_write_b32 v6, v158 offset:9696
	ds_write_b32 v6, v159 offset:10224
	ds_write_b32 v6, v160 offset:256
	ds_write_b32 v6, v161 offset:784
	ds_write_b32 v6, v162 offset:1312
	ds_write_b32 v6, v163 offset:1840
	ds_write_b32 v6, v164 offset:8704
	ds_write_b32 v6, v165 offset:9232
	ds_write_b32 v6, v166 offset:9760
	ds_write_b32 v6, v167 offset:10288
	ds_write_b32 v6, v168 offset:320
	ds_write_b32 v6, v169 offset:848
	ds_write_b32 v6, v170 offset:1376
	ds_write_b32 v6, v171 offset:1904
	ds_write_b32 v6, v172 offset:8768
	ds_write_b32 v6, v173 offset:9296
	ds_write_b32 v6, v174 offset:9824
	ds_write_b32 v6, v175 offset:10352
	ds_write_b32 v6, v176 offset:384
	ds_write_b32 v6, v177 offset:912
	ds_write_b32 v6, v178 offset:1440
	ds_write_b32 v6, v179 offset:1968
	ds_write_b32 v6, v180 offset:8832
	ds_write_b32 v6, v181 offset:9360
	ds_write_b32 v6, v182 offset:9888
	ds_write_b32 v6, v183 offset:10416
	ds_write_b32 v6, v184 offset:448
	ds_write_b32 v6, v185 offset:976
	ds_write_b32 v6, v186 offset:1504
	ds_write_b32 v6, v187 offset:2032
	s_nop 4
	ds_write_b32 v6, v188 offset:8896
	ds_write_b32 v6, v189 offset:9424
	ds_write_b32 v6, v190 offset:9952
	ds_write_b32 v6, v191 offset:10480
	v_mov_b32_e32 v192, 0
	v_mov_b32_e32 v193, 0
	s_waitcnt lgkmcnt(0)
	s_cmp_eq_u32 s55, 0
	s_cselect_b32 s100, 0, 16368
	s_mov_b32 s101, 0xfffffdf0
	s_cselect_b32 s101, 528, s101
	v_add_u32_e32 v13, s100, v7
	ds_read_b64 v[128:129], v13
	v_add_u32_e32 v13, s101, v13
	ds_read_b64 v[130:131], v13
	v_add_u32_e32 v13, s101, v13
	ds_read_b64 v[132:133], v13
	v_add_u32_e32 v13, s101, v13
	ds_read_b64 v[134:135], v13
	v_add_u32_e32 v13, s101, v13
	ds_read_b64 v[136:137], v13
	v_add_u32_e32 v13, s101, v13
	ds_read_b64 v[138:139], v13
	v_add_u32_e32 v13, s101, v13
	ds_read_b64 v[140:141], v13
	v_add_u32_e32 v13, s101, v13
	ds_read_b64 v[142:143], v13
	v_add_u32_e32 v13, s101, v13
	ds_read_b64 v[144:145], v13
	v_add_u32_e32 v13, s101, v13
	ds_read_b64 v[146:147], v13
	v_add_u32_e32 v13, s101, v13
	ds_read_b64 v[148:149], v13
	v_add_u32_e32 v13, s101, v13
	ds_read_b64 v[150:151], v13
	v_add_u32_e32 v13, s101, v13
	ds_read_b64 v[152:153], v13
	v_add_u32_e32 v13, s101, v13
	ds_read_b64 v[154:155], v13
	v_add_u32_e32 v13, s101, v13
	ds_read_b64 v[156:157], v13
	v_add_u32_e32 v13, s101, v13
	ds_read_b64 v[158:159], v13
	v_add_u32_e32 v13, s101, v13
	s_waitcnt lgkmcnt(15)
	v_mul_f32_e32 v194, v119, v193
	v_mul_f32_e32 v195, v119, v192
	v_fma_f32 v0, v118, v192, -v194
	v_fma_f32 v1, v118, v193, v195
	v_add_f32_e32 v192, v0, v128
	v_add_f32_e32 v193, v1, v129
	s_waitcnt lgkmcnt(14)
	v_mul_f32_e32 v194, v119, v193
	v_mul_f32_e32 v195, v119, v192
	v_fma_f32 v0, v118, v192, -v194
	v_fma_f32 v1, v118, v193, v195
	v_add_f32_e32 v192, v0, v130
	v_add_f32_e32 v193, v1, v131
	s_waitcnt lgkmcnt(13)
	v_mul_f32_e32 v194, v119, v193
	v_mul_f32_e32 v195, v119, v192
	v_fma_f32 v0, v118, v192, -v194
	v_fma_f32 v1, v118, v193, v195
	v_add_f32_e32 v192, v0, v132
	v_add_f32_e32 v193, v1, v133
	s_waitcnt lgkmcnt(12)
	v_mul_f32_e32 v194, v119, v193
	v_mul_f32_e32 v195, v119, v192
	v_fma_f32 v0, v118, v192, -v194
	v_fma_f32 v1, v118, v193, v195
	v_add_f32_e32 v192, v0, v134
	v_add_f32_e32 v193, v1, v135
	s_waitcnt lgkmcnt(11)
	v_mul_f32_e32 v194, v119, v193
	v_mul_f32_e32 v195, v119, v192
	v_fma_f32 v0, v118, v192, -v194
	v_fma_f32 v1, v118, v193, v195
	v_add_f32_e32 v192, v0, v136
	v_add_f32_e32 v193, v1, v137
	s_waitcnt lgkmcnt(10)
	v_mul_f32_e32 v194, v119, v193
	v_mul_f32_e32 v195, v119, v192
	v_fma_f32 v0, v118, v192, -v194
	v_fma_f32 v1, v118, v193, v195
	v_add_f32_e32 v192, v0, v138
	v_add_f32_e32 v193, v1, v139
	s_waitcnt lgkmcnt(9)
	v_mul_f32_e32 v194, v119, v193
	v_mul_f32_e32 v195, v119, v192
	v_fma_f32 v0, v118, v192, -v194
	v_fma_f32 v1, v118, v193, v195
	v_add_f32_e32 v192, v0, v140
	v_add_f32_e32 v193, v1, v141
	s_waitcnt lgkmcnt(8)
	v_mul_f32_e32 v194, v119, v193
	v_mul_f32_e32 v195, v119, v192
	v_fma_f32 v0, v118, v192, -v194
	v_fma_f32 v1, v118, v193, v195
	v_add_f32_e32 v192, v0, v142
	v_add_f32_e32 v193, v1, v143
	ds_read_b64 v[128:129], v13
	v_add_u32_e32 v13, s101, v13
	ds_read_b64 v[130:131], v13
	v_add_u32_e32 v13, s101, v13
	ds_read_b64 v[132:133], v13
	v_add_u32_e32 v13, s101, v13
	ds_read_b64 v[134:135], v13
	v_add_u32_e32 v13, s101, v13
	ds_read_b64 v[136:137], v13
	v_add_u32_e32 v13, s101, v13
	ds_read_b64 v[138:139], v13
	v_add_u32_e32 v13, s101, v13
	ds_read_b64 v[140:141], v13
	v_add_u32_e32 v13, s101, v13
	ds_read_b64 v[142:143], v13
	v_add_u32_e32 v13, s101, v13
	s_waitcnt lgkmcnt(15)
	v_mul_f32_e32 v194, v119, v193
	v_mul_f32_e32 v195, v119, v192
	v_fma_f32 v0, v118, v192, -v194
	v_fma_f32 v1, v118, v193, v195
	v_add_f32_e32 v192, v0, v144
	v_add_f32_e32 v193, v1, v145
	s_waitcnt lgkmcnt(14)
	v_mul_f32_e32 v194, v119, v193
	v_mul_f32_e32 v195, v119, v192
	v_fma_f32 v0, v118, v192, -v194
	v_fma_f32 v1, v118, v193, v195
	v_add_f32_e32 v192, v0, v146
	v_add_f32_e32 v193, v1, v147
	s_waitcnt lgkmcnt(13)
	v_mul_f32_e32 v194, v119, v193
	v_mul_f32_e32 v195, v119, v192
	v_fma_f32 v0, v118, v192, -v194
	v_fma_f32 v1, v118, v193, v195
	v_add_f32_e32 v192, v0, v148
	v_add_f32_e32 v193, v1, v149
	s_waitcnt lgkmcnt(12)
	v_mul_f32_e32 v194, v119, v193
	v_mul_f32_e32 v195, v119, v192
	v_fma_f32 v0, v118, v192, -v194
	v_fma_f32 v1, v118, v193, v195
	v_add_f32_e32 v192, v0, v150
	v_add_f32_e32 v193, v1, v151
	s_waitcnt lgkmcnt(11)
	v_mul_f32_e32 v194, v119, v193
	v_mul_f32_e32 v195, v119, v192
	v_fma_f32 v0, v118, v192, -v194
	v_fma_f32 v1, v118, v193, v195
	v_add_f32_e32 v192, v0, v152
	v_add_f32_e32 v193, v1, v153
	s_waitcnt lgkmcnt(10)
	v_mul_f32_e32 v194, v119, v193
	v_mul_f32_e32 v195, v119, v192
	v_fma_f32 v0, v118, v192, -v194
	v_fma_f32 v1, v118, v193, v195
	v_add_f32_e32 v192, v0, v154
	v_add_f32_e32 v193, v1, v155
	s_waitcnt lgkmcnt(9)
	v_mul_f32_e32 v194, v119, v193
	v_mul_f32_e32 v195, v119, v192
	v_fma_f32 v0, v118, v192, -v194
	v_fma_f32 v1, v118, v193, v195
	v_add_f32_e32 v192, v0, v156
	v_add_f32_e32 v193, v1, v157
	s_waitcnt lgkmcnt(8)
	v_mul_f32_e32 v194, v119, v193
	v_mul_f32_e32 v195, v119, v192
	v_fma_f32 v0, v118, v192, -v194
	v_fma_f32 v1, v118, v193, v195
	v_add_f32_e32 v192, v0, v158
	v_add_f32_e32 v193, v1, v159
	ds_read_b64 v[144:145], v13
	v_add_u32_e32 v13, s101, v13
	ds_read_b64 v[146:147], v13
	v_add_u32_e32 v13, s101, v13
	ds_read_b64 v[148:149], v13
	v_add_u32_e32 v13, s101, v13
	ds_read_b64 v[150:151], v13
	v_add_u32_e32 v13, s101, v13
	ds_read_b64 v[152:153], v13
	v_add_u32_e32 v13, s101, v13
	ds_read_b64 v[154:155], v13
	v_add_u32_e32 v13, s101, v13
	ds_read_b64 v[156:157], v13
	v_add_u32_e32 v13, s101, v13
	ds_read_b64 v[158:159], v13
	v_add_u32_e32 v13, s101, v13
	s_waitcnt lgkmcnt(15)
	v_mul_f32_e32 v194, v119, v193
	v_mul_f32_e32 v195, v119, v192
	v_fma_f32 v0, v118, v192, -v194
	v_fma_f32 v1, v118, v193, v195
	v_add_f32_e32 v192, v0, v128
	v_add_f32_e32 v193, v1, v129
	s_waitcnt lgkmcnt(14)
	v_mul_f32_e32 v194, v119, v193
	v_mul_f32_e32 v195, v119, v192
	v_fma_f32 v0, v118, v192, -v194
	v_fma_f32 v1, v118, v193, v195
	v_add_f32_e32 v192, v0, v130
	v_add_f32_e32 v193, v1, v131
	s_waitcnt lgkmcnt(13)
	v_mul_f32_e32 v194, v119, v193
	v_mul_f32_e32 v195, v119, v192
	v_fma_f32 v0, v118, v192, -v194
	v_fma_f32 v1, v118, v193, v195
	v_add_f32_e32 v192, v0, v132
	v_add_f32_e32 v193, v1, v133
	s_waitcnt lgkmcnt(12)
	v_mul_f32_e32 v194, v119, v193
	v_mul_f32_e32 v195, v119, v192
	v_fma_f32 v0, v118, v192, -v194
	v_fma_f32 v1, v118, v193, v195
	v_add_f32_e32 v192, v0, v134
	v_add_f32_e32 v193, v1, v135
	s_waitcnt lgkmcnt(11)
	v_mul_f32_e32 v194, v119, v193
	v_mul_f32_e32 v195, v119, v192
	v_fma_f32 v0, v118, v192, -v194
	v_fma_f32 v1, v118, v193, v195
	v_add_f32_e32 v192, v0, v136
	v_add_f32_e32 v193, v1, v137
	s_waitcnt lgkmcnt(10)
	v_mul_f32_e32 v194, v119, v193
	v_mul_f32_e32 v195, v119, v192
	v_fma_f32 v0, v118, v192, -v194
	v_fma_f32 v1, v118, v193, v195
	v_add_f32_e32 v192, v0, v138
	v_add_f32_e32 v193, v1, v139
	s_waitcnt lgkmcnt(9)
	v_mul_f32_e32 v194, v119, v193
	v_mul_f32_e32 v195, v119, v192
	v_fma_f32 v0, v118, v192, -v194
	v_fma_f32 v1, v118, v193, v195
	v_add_f32_e32 v192, v0, v140
	v_add_f32_e32 v193, v1, v141
	s_waitcnt lgkmcnt(8)
	v_mul_f32_e32 v194, v119, v193
	v_mul_f32_e32 v195, v119, v192
	v_fma_f32 v0, v118, v192, -v194
	v_fma_f32 v1, v118, v193, v195
	v_add_f32_e32 v192, v0, v142
	v_add_f32_e32 v193, v1, v143
	s_waitcnt lgkmcnt(7)
	v_mul_f32_e32 v194, v119, v193
	v_mul_f32_e32 v195, v119, v192
	v_fma_f32 v0, v118, v192, -v194
	v_fma_f32 v1, v118, v193, v195
	v_add_f32_e32 v192, v0, v144
	v_add_f32_e32 v193, v1, v145
	s_waitcnt lgkmcnt(6)
	v_mul_f32_e32 v194, v119, v193
	v_mul_f32_e32 v195, v119, v192
	v_fma_f32 v0, v118, v192, -v194
	v_fma_f32 v1, v118, v193, v195
	v_add_f32_e32 v192, v0, v146
	v_add_f32_e32 v193, v1, v147
	s_waitcnt lgkmcnt(5)
	v_mul_f32_e32 v194, v119, v193
	v_mul_f32_e32 v195, v119, v192
	v_fma_f32 v0, v118, v192, -v194
	v_fma_f32 v1, v118, v193, v195
	v_add_f32_e32 v192, v0, v148
	v_add_f32_e32 v193, v1, v149
	s_waitcnt lgkmcnt(4)
	v_mul_f32_e32 v194, v119, v193
	v_mul_f32_e32 v195, v119, v192
	v_fma_f32 v0, v118, v192, -v194
	v_fma_f32 v1, v118, v193, v195
	v_add_f32_e32 v192, v0, v150
	v_add_f32_e32 v193, v1, v151
	s_waitcnt lgkmcnt(3)
	v_mul_f32_e32 v194, v119, v193
	v_mul_f32_e32 v195, v119, v192
	v_fma_f32 v0, v118, v192, -v194
	v_fma_f32 v1, v118, v193, v195
	v_add_f32_e32 v192, v0, v152
	v_add_f32_e32 v193, v1, v153
	s_waitcnt lgkmcnt(2)
	v_mul_f32_e32 v194, v119, v193
	v_mul_f32_e32 v195, v119, v192
	v_fma_f32 v0, v118, v192, -v194
	v_fma_f32 v1, v118, v193, v195
	v_add_f32_e32 v192, v0, v154
	v_add_f32_e32 v193, v1, v155
	s_waitcnt lgkmcnt(1)
	v_mul_f32_e32 v194, v119, v193
	v_mul_f32_e32 v195, v119, v192
	v_fma_f32 v0, v118, v192, -v194
	v_fma_f32 v1, v118, v193, v195
	v_add_f32_e32 v192, v0, v156
	v_add_f32_e32 v193, v1, v157
	s_waitcnt lgkmcnt(0)
	v_mul_f32_e32 v194, v119, v193
	v_mul_f32_e32 v195, v119, v192
	v_fma_f32 v0, v118, v192, -v194
	v_fma_f32 v1, v118, v193, v195
	v_add_f32_e32 v192, v0, v158
	v_add_f32_e32 v193, v1, v159
	global_store_dwordx2 v10, v[192:193], s[56:57]
	s_waitcnt vmcnt(0)
	v_cvt_pk_bf16_f32 v120, v20, v21
	v_cvt_pk_bf16_f32 v121, v22, v23
	v_cvt_pk_bf16_f32 v122, v24, v25
	v_cvt_pk_bf16_f32 v123, v26, v27
	v_cvt_pk_bf16_f32 v124, v28, v29
	v_cvt_pk_bf16_f32 v125, v30, v31
	v_cvt_pk_bf16_f32 v126, v32, v33
	v_cvt_pk_bf16_f32 v127, v34, v35
	s_nop 1
	v_mfma_f32_16x16x32_bf16 v[128:131], v[120:123], v[36:39], 0
	v_mfma_f32_16x16x32_bf16 v[132:135], v[124:127], v[36:39], 0
	v_mfma_f32_16x16x32_bf16 v[136:139], v[120:123], v[40:43], 0
	v_mfma_f32_16x16x32_bf16 v[140:143], v[124:127], v[40:43], 0
	v_mfma_f32_16x16x32_bf16 v[144:147], v[120:123], v[44:47], 0
	v_mfma_f32_16x16x32_bf16 v[148:151], v[124:127], v[44:47], 0
	v_mfma_f32_16x16x32_bf16 v[152:155], v[120:123], v[48:51], 0
	v_mfma_f32_16x16x32_bf16 v[156:159], v[124:127], v[48:51], 0
	v_mfma_f32_16x16x32_bf16 v[160:163], v[120:123], v[52:55], 0
	v_mfma_f32_16x16x32_bf16 v[164:167], v[124:127], v[52:55], 0
	v_mfma_f32_16x16x32_bf16 v[168:171], v[120:123], v[56:59], 0
	v_mfma_f32_16x16x32_bf16 v[172:175], v[124:127], v[56:59], 0
	v_mfma_f32_16x16x32_bf16 v[176:179], v[120:123], v[60:63], 0
	v_mfma_f32_16x16x32_bf16 v[180:183], v[124:127], v[60:63], 0
	v_mfma_f32_16x16x32_bf16 v[184:187], v[120:123], v[64:67], 0
	v_mfma_f32_16x16x32_bf16 v[188:191], v[124:127], v[64:67], 0
	ds_write_b32 v6, v128 offset:0
	ds_write_b32 v6, v129 offset:528
	ds_write_b32 v6, v130 offset:1056
	ds_write_b32 v6, v131 offset:1584
	ds_write_b32 v6, v132 offset:8448
	ds_write_b32 v6, v133 offset:8976
	ds_write_b32 v6, v134 offset:9504
	ds_write_b32 v6, v135 offset:10032
	ds_write_b32 v6, v136 offset:64
	ds_write_b32 v6, v137 offset:592
	ds_write_b32 v6, v138 offset:1120
	ds_write_b32 v6, v139 offset:1648
	ds_write_b32 v6, v140 offset:8512
	ds_write_b32 v6, v141 offset:9040
	ds_write_b32 v6, v142 offset:9568
	ds_write_b32 v6, v143 offset:10096
	ds_write_b32 v6, v144 offset:128
	ds_write_b32 v6, v145 offset:656
	ds_write_b32 v6, v146 offset:1184
	ds_write_b32 v6, v147 offset:1712
	ds_write_b32 v6, v148 offset:8576
	ds_write_b32 v6, v149 offset:9104
	ds_write_b32 v6, v150 offset:9632
	ds_write_b32 v6, v151 offset:10160
	ds_write_b32 v6, v152 offset:192
	ds_write_b32 v6, v153 offset:720
	ds_write_b32 v6, v154 offset:1248
	ds_write_b32 v6, v155 offset:1776
	ds_write_b32 v6, v156 offset:8640
	ds_write_b32 v6, v157 offset:9168
	ds_write_b32 v6, v158 offset:9696
	ds_write_b32 v6, v159 offset:10224
	ds_write_b32 v6, v160 offset:256
	ds_write_b32 v6, v161 offset:784
	ds_write_b32 v6, v162 offset:1312
	ds_write_b32 v6, v163 offset:1840
	ds_write_b32 v6, v164 offset:8704
	ds_write_b32 v6, v165 offset:9232
	ds_write_b32 v6, v166 offset:9760
	ds_write_b32 v6, v167 offset:10288
	ds_write_b32 v6, v168 offset:320
	ds_write_b32 v6, v169 offset:848
	ds_write_b32 v6, v170 offset:1376
	ds_write_b32 v6, v171 offset:1904
	ds_write_b32 v6, v172 offset:8768
	ds_write_b32 v6, v173 offset:9296
	ds_write_b32 v6, v174 offset:9824
	ds_write_b32 v6, v175 offset:10352
	ds_write_b32 v6, v176 offset:384
	ds_write_b32 v6, v177 offset:912
	ds_write_b32 v6, v178 offset:1440
	ds_write_b32 v6, v179 offset:1968
	ds_write_b32 v6, v180 offset:8832
	ds_write_b32 v6, v181 offset:9360
	ds_write_b32 v6, v182 offset:9888
	ds_write_b32 v6, v183 offset:10416
	ds_write_b32 v6, v184 offset:448
	ds_write_b32 v6, v185 offset:976
	ds_write_b32 v6, v186 offset:1504
	ds_write_b32 v6, v187 offset:2032
	s_nop 4
	ds_write_b32 v6, v188 offset:8896
	ds_write_b32 v6, v189 offset:9424
	ds_write_b32 v6, v190 offset:9952
	ds_write_b32 v6, v191 offset:10480
	v_mov_b32_e32 v192, 0
	v_mov_b32_e32 v193, 0
	s_waitcnt lgkmcnt(0)
	s_cmp_eq_u32 s54, 0
	s_cselect_b32 s100, 0, 16368
	s_mov_b32 s101, 0xfffffdf0
	s_cselect_b32 s101, 528, s101
	v_add_u32_e32 v13, s100, v7
	ds_read_b64 v[128:129], v13
	v_add_u32_e32 v13, s101, v13
	ds_read_b64 v[130:131], v13
	v_add_u32_e32 v13, s101, v13
	ds_read_b64 v[132:133], v13
	v_add_u32_e32 v13, s101, v13
	ds_read_b64 v[134:135], v13
	v_add_u32_e32 v13, s101, v13
	ds_read_b64 v[136:137], v13
	v_add_u32_e32 v13, s101, v13
	ds_read_b64 v[138:139], v13
	v_add_u32_e32 v13, s101, v13
	ds_read_b64 v[140:141], v13
	v_add_u32_e32 v13, s101, v13
	ds_read_b64 v[142:143], v13
	v_add_u32_e32 v13, s101, v13
	ds_read_b64 v[144:145], v13
	v_add_u32_e32 v13, s101, v13
	ds_read_b64 v[146:147], v13
	v_add_u32_e32 v13, s101, v13
	ds_read_b64 v[148:149], v13
	v_add_u32_e32 v13, s101, v13
	ds_read_b64 v[150:151], v13
	v_add_u32_e32 v13, s101, v13
	ds_read_b64 v[152:153], v13
	v_add_u32_e32 v13, s101, v13
	ds_read_b64 v[154:155], v13
	v_add_u32_e32 v13, s101, v13
	ds_read_b64 v[156:157], v13
	v_add_u32_e32 v13, s101, v13
	ds_read_b64 v[158:159], v13
	v_add_u32_e32 v13, s101, v13
	s_waitcnt lgkmcnt(15)
	v_mul_f32_e32 v194, v69, v193
	v_mul_f32_e32 v195, v69, v192
	v_fma_f32 v0, v68, v192, -v194
	v_fma_f32 v1, v68, v193, v195
	v_add_f32_e32 v192, v0, v128
	v_add_f32_e32 v193, v1, v129
	s_waitcnt lgkmcnt(14)
	v_mul_f32_e32 v194, v69, v193
	v_mul_f32_e32 v195, v69, v192
	v_fma_f32 v0, v68, v192, -v194
	v_fma_f32 v1, v68, v193, v195
	v_add_f32_e32 v192, v0, v130
	v_add_f32_e32 v193, v1, v131
	s_waitcnt lgkmcnt(13)
	v_mul_f32_e32 v194, v69, v193
	v_mul_f32_e32 v195, v69, v192
	v_fma_f32 v0, v68, v192, -v194
	v_fma_f32 v1, v68, v193, v195
	v_add_f32_e32 v192, v0, v132
	v_add_f32_e32 v193, v1, v133
	s_waitcnt lgkmcnt(12)
	v_mul_f32_e32 v194, v69, v193
	v_mul_f32_e32 v195, v69, v192
	v_fma_f32 v0, v68, v192, -v194
	v_fma_f32 v1, v68, v193, v195
	v_add_f32_e32 v192, v0, v134
	v_add_f32_e32 v193, v1, v135
	s_waitcnt lgkmcnt(11)
	v_mul_f32_e32 v194, v69, v193
	v_mul_f32_e32 v195, v69, v192
	v_fma_f32 v0, v68, v192, -v194
	v_fma_f32 v1, v68, v193, v195
	v_add_f32_e32 v192, v0, v136
	v_add_f32_e32 v193, v1, v137
	s_waitcnt lgkmcnt(10)
	v_mul_f32_e32 v194, v69, v193
	v_mul_f32_e32 v195, v69, v192
	v_fma_f32 v0, v68, v192, -v194
	v_fma_f32 v1, v68, v193, v195
	v_add_f32_e32 v192, v0, v138
	v_add_f32_e32 v193, v1, v139
	s_waitcnt lgkmcnt(9)
	v_mul_f32_e32 v194, v69, v193
	v_mul_f32_e32 v195, v69, v192
	v_fma_f32 v0, v68, v192, -v194
	v_fma_f32 v1, v68, v193, v195
	v_add_f32_e32 v192, v0, v140
	v_add_f32_e32 v193, v1, v141
	s_waitcnt lgkmcnt(8)
	v_mul_f32_e32 v194, v69, v193
	v_mul_f32_e32 v195, v69, v192
	v_fma_f32 v0, v68, v192, -v194
	v_fma_f32 v1, v68, v193, v195
	v_add_f32_e32 v192, v0, v142
	v_add_f32_e32 v193, v1, v143
	ds_read_b64 v[128:129], v13
	v_add_u32_e32 v13, s101, v13
	ds_read_b64 v[130:131], v13
	v_add_u32_e32 v13, s101, v13
	ds_read_b64 v[132:133], v13
	v_add_u32_e32 v13, s101, v13
	ds_read_b64 v[134:135], v13
	v_add_u32_e32 v13, s101, v13
	ds_read_b64 v[136:137], v13
	v_add_u32_e32 v13, s101, v13
	ds_read_b64 v[138:139], v13
	v_add_u32_e32 v13, s101, v13
	ds_read_b64 v[140:141], v13
	v_add_u32_e32 v13, s101, v13
	ds_read_b64 v[142:143], v13
	v_add_u32_e32 v13, s101, v13
	s_waitcnt lgkmcnt(15)
	v_mul_f32_e32 v194, v69, v193
	v_mul_f32_e32 v195, v69, v192
	v_fma_f32 v0, v68, v192, -v194
	v_fma_f32 v1, v68, v193, v195
	v_add_f32_e32 v192, v0, v144
	v_add_f32_e32 v193, v1, v145
	s_waitcnt lgkmcnt(14)
	v_mul_f32_e32 v194, v69, v193
	v_mul_f32_e32 v195, v69, v192
	v_fma_f32 v0, v68, v192, -v194
	v_fma_f32 v1, v68, v193, v195
	v_add_f32_e32 v192, v0, v146
	v_add_f32_e32 v193, v1, v147
	s_waitcnt lgkmcnt(13)
	v_mul_f32_e32 v194, v69, v193
	v_mul_f32_e32 v195, v69, v192
	v_fma_f32 v0, v68, v192, -v194
	v_fma_f32 v1, v68, v193, v195
	v_add_f32_e32 v192, v0, v148
	v_add_f32_e32 v193, v1, v149
	s_waitcnt lgkmcnt(12)
	v_mul_f32_e32 v194, v69, v193
	v_mul_f32_e32 v195, v69, v192
	v_fma_f32 v0, v68, v192, -v194
	v_fma_f32 v1, v68, v193, v195
	v_add_f32_e32 v192, v0, v150
	v_add_f32_e32 v193, v1, v151
	s_waitcnt lgkmcnt(11)
	v_mul_f32_e32 v194, v69, v193
	v_mul_f32_e32 v195, v69, v192
	v_fma_f32 v0, v68, v192, -v194
	v_fma_f32 v1, v68, v193, v195
	v_add_f32_e32 v192, v0, v152
	v_add_f32_e32 v193, v1, v153
	s_waitcnt lgkmcnt(10)
	v_mul_f32_e32 v194, v69, v193
	v_mul_f32_e32 v195, v69, v192
	v_fma_f32 v0, v68, v192, -v194
	v_fma_f32 v1, v68, v193, v195
	v_add_f32_e32 v192, v0, v154
	v_add_f32_e32 v193, v1, v155
	s_waitcnt lgkmcnt(9)
	v_mul_f32_e32 v194, v69, v193
	v_mul_f32_e32 v195, v69, v192
	v_fma_f32 v0, v68, v192, -v194
	v_fma_f32 v1, v68, v193, v195
	v_add_f32_e32 v192, v0, v156
	v_add_f32_e32 v193, v1, v157
	s_waitcnt lgkmcnt(8)
	v_mul_f32_e32 v194, v69, v193
	v_mul_f32_e32 v195, v69, v192
	v_fma_f32 v0, v68, v192, -v194
	v_fma_f32 v1, v68, v193, v195
	v_add_f32_e32 v192, v0, v158
	v_add_f32_e32 v193, v1, v159
	ds_read_b64 v[144:145], v13
	v_add_u32_e32 v13, s101, v13
	ds_read_b64 v[146:147], v13
	v_add_u32_e32 v13, s101, v13
	ds_read_b64 v[148:149], v13
	v_add_u32_e32 v13, s101, v13
	ds_read_b64 v[150:151], v13
	v_add_u32_e32 v13, s101, v13
	ds_read_b64 v[152:153], v13
	v_add_u32_e32 v13, s101, v13
	ds_read_b64 v[154:155], v13
	v_add_u32_e32 v13, s101, v13
	ds_read_b64 v[156:157], v13
	v_add_u32_e32 v13, s101, v13
	ds_read_b64 v[158:159], v13
	v_add_u32_e32 v13, s101, v13
	s_waitcnt lgkmcnt(15)
	v_mul_f32_e32 v194, v69, v193
	v_mul_f32_e32 v195, v69, v192
	v_fma_f32 v0, v68, v192, -v194
	v_fma_f32 v1, v68, v193, v195
	v_add_f32_e32 v192, v0, v128
	v_add_f32_e32 v193, v1, v129
	s_waitcnt lgkmcnt(14)
	v_mul_f32_e32 v194, v69, v193
	v_mul_f32_e32 v195, v69, v192
	v_fma_f32 v0, v68, v192, -v194
	v_fma_f32 v1, v68, v193, v195
	v_add_f32_e32 v192, v0, v130
	v_add_f32_e32 v193, v1, v131
	s_waitcnt lgkmcnt(13)
	v_mul_f32_e32 v194, v69, v193
	v_mul_f32_e32 v195, v69, v192
	v_fma_f32 v0, v68, v192, -v194
	v_fma_f32 v1, v68, v193, v195
	v_add_f32_e32 v192, v0, v132
	v_add_f32_e32 v193, v1, v133
	s_waitcnt lgkmcnt(12)
	v_mul_f32_e32 v194, v69, v193
	v_mul_f32_e32 v195, v69, v192
	v_fma_f32 v0, v68, v192, -v194
	v_fma_f32 v1, v68, v193, v195
	v_add_f32_e32 v192, v0, v134
	v_add_f32_e32 v193, v1, v135
	s_waitcnt lgkmcnt(11)
	v_mul_f32_e32 v194, v69, v193
	v_mul_f32_e32 v195, v69, v192
	v_fma_f32 v0, v68, v192, -v194
	v_fma_f32 v1, v68, v193, v195
	v_add_f32_e32 v192, v0, v136
	v_add_f32_e32 v193, v1, v137
	s_waitcnt lgkmcnt(10)
	v_mul_f32_e32 v194, v69, v193
	v_mul_f32_e32 v195, v69, v192
	v_fma_f32 v0, v68, v192, -v194
	v_fma_f32 v1, v68, v193, v195
	v_add_f32_e32 v192, v0, v138
	v_add_f32_e32 v193, v1, v139
	s_waitcnt lgkmcnt(9)
	v_mul_f32_e32 v194, v69, v193
	v_mul_f32_e32 v195, v69, v192
	v_fma_f32 v0, v68, v192, -v194
	v_fma_f32 v1, v68, v193, v195
	v_add_f32_e32 v192, v0, v140
	v_add_f32_e32 v193, v1, v141
	s_waitcnt lgkmcnt(8)
	v_mul_f32_e32 v194, v69, v193
	v_mul_f32_e32 v195, v69, v192
	v_fma_f32 v0, v68, v192, -v194
	v_fma_f32 v1, v68, v193, v195
	v_add_f32_e32 v192, v0, v142
	v_add_f32_e32 v193, v1, v143
	s_waitcnt lgkmcnt(7)
	v_mul_f32_e32 v194, v69, v193
	v_mul_f32_e32 v195, v69, v192
	v_fma_f32 v0, v68, v192, -v194
	v_fma_f32 v1, v68, v193, v195
	v_add_f32_e32 v192, v0, v144
	v_add_f32_e32 v193, v1, v145
	s_waitcnt lgkmcnt(6)
	v_mul_f32_e32 v194, v69, v193
	v_mul_f32_e32 v195, v69, v192
	v_fma_f32 v0, v68, v192, -v194
	v_fma_f32 v1, v68, v193, v195
	v_add_f32_e32 v192, v0, v146
	v_add_f32_e32 v193, v1, v147
	s_waitcnt lgkmcnt(5)
	v_mul_f32_e32 v194, v69, v193
	v_mul_f32_e32 v195, v69, v192
	v_fma_f32 v0, v68, v192, -v194
	v_fma_f32 v1, v68, v193, v195
	v_add_f32_e32 v192, v0, v148
	v_add_f32_e32 v193, v1, v149
	s_waitcnt lgkmcnt(4)
	v_mul_f32_e32 v194, v69, v193
	v_mul_f32_e32 v195, v69, v192
	v_fma_f32 v0, v68, v192, -v194
	v_fma_f32 v1, v68, v193, v195
	v_add_f32_e32 v192, v0, v150
	v_add_f32_e32 v193, v1, v151
	s_waitcnt lgkmcnt(3)
	v_mul_f32_e32 v194, v69, v193
	v_mul_f32_e32 v195, v69, v192
	v_fma_f32 v0, v68, v192, -v194
	v_fma_f32 v1, v68, v193, v195
	v_add_f32_e32 v192, v0, v152
	v_add_f32_e32 v193, v1, v153
	s_waitcnt lgkmcnt(2)
	v_mul_f32_e32 v194, v69, v193
	v_mul_f32_e32 v195, v69, v192
	v_fma_f32 v0, v68, v192, -v194
	v_fma_f32 v1, v68, v193, v195
	v_add_f32_e32 v192, v0, v154
	v_add_f32_e32 v193, v1, v155
	s_waitcnt lgkmcnt(1)
	v_mul_f32_e32 v194, v69, v193
	v_mul_f32_e32 v195, v69, v192
	v_fma_f32 v0, v68, v192, -v194
	v_fma_f32 v1, v68, v193, v195
	v_add_f32_e32 v192, v0, v156
	v_add_f32_e32 v193, v1, v157
	s_waitcnt lgkmcnt(0)
	v_mul_f32_e32 v194, v69, v193
	v_mul_f32_e32 v195, v69, v192
	v_fma_f32 v0, v68, v192, -v194
	v_fma_f32 v1, v68, v193, v195
	v_add_f32_e32 v192, v0, v158
	v_add_f32_e32 v193, v1, v159
	global_store_dwordx2 v10, v[192:193], s[50:51]
	s_waitcnt vmcnt(0) lgkmcnt(0)
	s_branch .Ls5l_back

.Lgm_glu_join:
	s_waitcnt lgkmcnt(13)
	v_mfma_f32_16x16x32_bf16 v[4:7], v[100:103], v[124:127], v[4:7]
	v_mfma_f32_16x16x32_bf16 v[20:23], v[104:107], v[124:127], v[20:23]
	v_mfma_f32_16x16x32_bf16 v[36:39], v[108:111], v[124:127], v[36:39]
	v_mfma_f32_16x16x32_bf16 v[52:55], v[112:115], v[124:127], v[52:55]
	v_mfma_f32_16x16x32_bf16 v[68:71], v[116:119], v[124:127], v[68:71]
	v_mfma_f32_16x16x32_bf16 v[84:87], v[120:123], v[124:127], v[84:87]
	s_waitcnt lgkmcnt(12)
	v_mfma_f32_16x16x32_bf16 v[8:11], v[100:103], v[128:131], v[8:11]
	v_mfma_f32_16x16x32_bf16 v[24:27], v[104:107], v[128:131], v[24:27]
	v_mfma_f32_16x16x32_bf16 v[40:43], v[108:111], v[128:131], v[40:43]
	v_mfma_f32_16x16x32_bf16 v[56:59], v[112:115], v[128:131], v[56:59]
	v_mfma_f32_16x16x32_bf16 v[72:75], v[116:119], v[128:131], v[72:75]
	v_mfma_f32_16x16x32_bf16 v[88:91], v[120:123], v[128:131], v[88:91]
	s_waitcnt lgkmcnt(11)
	v_mfma_f32_16x16x32_bf16 v[12:15], v[100:103], v[132:135], v[12:15]
	v_mfma_f32_16x16x32_bf16 v[28:31], v[104:107], v[132:135], v[28:31]
	v_mfma_f32_16x16x32_bf16 v[44:47], v[108:111], v[132:135], v[44:47]
	v_mfma_f32_16x16x32_bf16 v[60:63], v[112:115], v[132:135], v[60:63]
	v_mfma_f32_16x16x32_bf16 v[76:79], v[116:119], v[132:135], v[76:79]
	v_mfma_f32_16x16x32_bf16 v[92:95], v[120:123], v[132:135], v[92:95]
	s_waitcnt lgkmcnt(10)
	v_mfma_f32_16x16x32_bf16 v[16:19], v[100:103], v[136:139], v[16:19]
	v_mfma_f32_16x16x32_bf16 v[32:35], v[104:107], v[136:139], v[32:35]
	v_mfma_f32_16x16x32_bf16 v[48:51], v[108:111], v[136:139], v[48:51]
	v_mfma_f32_16x16x32_bf16 v[64:67], v[112:115], v[136:139], v[64:67]
	v_mfma_f32_16x16x32_bf16 v[80:83], v[116:119], v[136:139], v[80:83]
	v_mfma_f32_16x16x32_bf16 v[96:99], v[120:123], v[136:139], v[96:99]
	s_waitcnt lgkmcnt(0)
	s_add_u32 s34, s34, 1
	s_add_u32 s31, s31, 1
	s_cmp_lt_u32 s34, 4
	s_cbranch_scc1 .Lgm_glu_rot
	v_mfma_f32_16x16x32_bf16 v[4:7], v[140:143], v[164:167], v[4:7]
	v_mfma_f32_16x16x32_bf16 v[20:23], v[144:147], v[164:167], v[20:23]
	v_mfma_f32_16x16x32_bf16 v[36:39], v[148:151], v[164:167], v[36:39]
	v_mfma_f32_16x16x32_bf16 v[52:55], v[152:155], v[164:167], v[52:55]
	v_mfma_f32_16x16x32_bf16 v[68:71], v[156:159], v[164:167], v[68:71]
	v_mfma_f32_16x16x32_bf16 v[84:87], v[160:163], v[164:167], v[84:87]
	v_mfma_f32_16x16x32_bf16 v[8:11], v[140:143], v[168:171], v[8:11]
	v_mfma_f32_16x16x32_bf16 v[24:27], v[144:147], v[168:171], v[24:27]
	v_mfma_f32_16x16x32_bf16 v[40:43], v[148:151], v[168:171], v[40:43]
	v_mfma_f32_16x16x32_bf16 v[56:59], v[152:155], v[168:171], v[56:59]
	v_mfma_f32_16x16x32_bf16 v[72:75], v[156:159], v[168:171], v[72:75]
	v_mfma_f32_16x16x32_bf16 v[88:91], v[160:163], v[168:171], v[88:91]
	v_mfma_f32_16x16x32_bf16 v[12:15], v[140:143], v[172:175], v[12:15]
	v_mfma_f32_16x16x32_bf16 v[28:31], v[144:147], v[172:175], v[28:31]
	v_mfma_f32_16x16x32_bf16 v[44:47], v[148:151], v[172:175], v[44:47]
	v_mfma_f32_16x16x32_bf16 v[60:63], v[152:155], v[172:175], v[60:63]
	v_mfma_f32_16x16x32_bf16 v[76:79], v[156:159], v[172:175], v[76:79]
	v_mfma_f32_16x16x32_bf16 v[92:95], v[160:163], v[172:175], v[92:95]
	v_mfma_f32_16x16x32_bf16 v[16:19], v[140:143], v[176:179], v[16:19]
	v_mfma_f32_16x16x32_bf16 v[32:35], v[144:147], v[176:179], v[32:35]
	v_mfma_f32_16x16x32_bf16 v[48:51], v[148:151], v[176:179], v[48:51]
	v_mfma_f32_16x16x32_bf16 v[64:67], v[152:155], v[176:179], v[64:67]
	v_mfma_f32_16x16x32_bf16 v[80:83], v[156:159], v[176:179], v[80:83]
	v_mfma_f32_16x16x32_bf16 v[96:99], v[160:163], v[176:179], v[96:99]
	s_and_b32 s6, s35, 31
	s_mul_i32 s6, s6, 192
	s_lshr_b32 s7, s35, 5
	s_lshl_b32 s7, s7, 7
	s_nop 7
	s_mul_i32 s4, s6, 0x800
	s_lshl_b32 s5, s7, 1
	s_add_u32 s4, s4, s5
	v_add_u32_e32 v197, s4, v205
	v_lshl_add_u32 v195, s7, 2, v191
	global_load_dwordx4 v[148:151], v195, s[100:101]
	s_lshl_b32 s4, s6, 9
	s_add_u32 s4, s4, s5
	v_lshlrev_b32_e32 v194, 9, v190
	v_lshl_add_u32 v194, v193, 1, v194
	v_add_u32_e32 v194, s4, v194
	global_load_dwordx2 v[100:101], v194, s[98:99]
	v_add_u32_e32 v194, 0x800, v194
	global_load_dwordx2 v[102:103], v194, s[98:99]
	v_add_u32_e32 v194, 0x800, v194
	global_load_dwordx2 v[104:105], v194, s[98:99]
	v_add_u32_e32 v194, 0x800, v194
	global_load_dwordx2 v[106:107], v194, s[98:99]
	v_add_u32_e32 v194, 0x800, v194
	global_load_dwordx2 v[108:109], v194, s[98:99]
	v_add_u32_e32 v194, 0x800, v194
	global_load_dwordx2 v[110:111], v194, s[98:99]
	v_add_u32_e32 v194, 0x800, v194
	global_load_dwordx2 v[112:113], v194, s[98:99]
	v_add_u32_e32 v194, 0x800, v194
	global_load_dwordx2 v[114:115], v194, s[98:99]
	v_add_u32_e32 v194, 0x800, v194
	global_load_dwordx2 v[116:117], v194, s[98:99]
	v_add_u32_e32 v194, 0x800, v194
	global_load_dwordx2 v[118:119], v194, s[98:99]
	v_add_u32_e32 v194, 0x800, v194
	global_load_dwordx2 v[120:121], v194, s[98:99]
	v_add_u32_e32 v194, 0x800, v194
	global_load_dwordx2 v[122:123], v194, s[98:99]
	v_add_u32_e32 v194, 0x800, v194
	global_load_dwordx2 v[124:125], v194, s[98:99]
	v_add_u32_e32 v194, 0x800, v194
	global_load_dwordx2 v[126:127], v194, s[98:99]
	v_add_u32_e32 v194, 0x800, v194
	global_load_dwordx2 v[128:129], v194, s[98:99]
	v_add_u32_e32 v194, 0x800, v194
	global_load_dwordx2 v[130:131], v194, s[98:99]
	v_add_u32_e32 v194, 0x800, v194
	global_load_dwordx2 v[132:133], v194, s[98:99]
	v_add_u32_e32 v194, 0x800, v194
	global_load_dwordx2 v[134:135], v194, s[98:99]
	v_add_u32_e32 v194, 0x800, v194
	global_load_dwordx2 v[136:137], v194, s[98:99]
	v_add_u32_e32 v194, 0x800, v194
	global_load_dwordx2 v[138:139], v194, s[98:99]
	v_add_u32_e32 v194, 0x800, v194
	global_load_dwordx2 v[140:141], v194, s[98:99]
	v_add_u32_e32 v194, 0x800, v194
	global_load_dwordx2 v[142:143], v194, s[98:99]
	v_add_u32_e32 v194, 0x800, v194
	global_load_dwordx2 v[144:145], v194, s[98:99]
	v_add_u32_e32 v194, 0x800, v194
	global_load_dwordx2 v[146:147], v194, s[98:99]
	s_mov_b32 s4, 0
.Lgm_glu_glu_ep4:
	ds_write_b32 v203, v4 offset:0
	ds_write_b32 v203, v5 offset:272
	ds_write_b32 v203, v6 offset:544
	ds_write_b32 v203, v7 offset:816
	ds_write_b32 v203, v8 offset:64
	ds_write_b32 v203, v9 offset:336
	ds_write_b32 v203, v10 offset:608
	ds_write_b32 v203, v11 offset:880
	ds_write_b32 v203, v12 offset:128
	ds_write_b32 v203, v13 offset:400
	ds_write_b32 v203, v14 offset:672
	ds_write_b32 v203, v15 offset:944
	ds_write_b32 v203, v16 offset:192
	ds_write_b32 v203, v17 offset:464
	ds_write_b32 v203, v18 offset:736
	ds_write_b32 v203, v19 offset:1008
	s_waitcnt lgkmcnt(0)
	ds_read_b128 v[156:159], v204 offset:0
	ds_read_b128 v[160:163], v204 offset:1088
	ds_read_b128 v[164:167], v204 offset:2176
	ds_read_b128 v[168:171], v204 offset:3264
	s_waitcnt vmcnt(23)
	s_waitcnt lgkmcnt(3)
	v_add_f32_e32 v156, v156, v148
	v_add_f32_e32 v157, v157, v149
	v_add_f32_e32 v158, v158, v150
	v_add_f32_e32 v159, v159, v151
	v_mul_f32_e32 v156, 0xbfb8aa3b, v156
	v_mul_f32_e32 v157, 0xbfb8aa3b, v157
	v_mul_f32_e32 v158, 0xbfb8aa3b, v158
	v_mul_f32_e32 v159, 0xbfb8aa3b, v159
	v_exp_f32_e32 v156, v156
	v_exp_f32_e32 v157, v157
	v_exp_f32_e32 v158, v158
	v_exp_f32_e32 v159, v159
	v_lshlrev_b32_e32 v172, 16, v100
	v_and_b32_e32 v173, s28, v100
	v_lshlrev_b32_e32 v174, 16, v101
	v_and_b32_e32 v175, s28, v101
	v_add_f32_e32 v156, 1.0, v156
	v_add_f32_e32 v157, 1.0, v157
	v_add_f32_e32 v158, 1.0, v158
	v_add_f32_e32 v159, 1.0, v159
	v_div_scale_f32 v0, vcc, v156, v156, 1.0
	v_rcp_f32_e32 v1, v0
	s_nop 0
	v_fma_f32 v3, -v0, v1, 1.0
	v_fmac_f32_e32 v1, v3, v1
	v_div_scale_f32 v3, vcc, 1.0, v156, 1.0
	v_mul_f32_e32 v152, v3, v1
	v_fma_f32 v153, -v0, v152, v3
	v_fmac_f32_e32 v152, v153, v1
	v_fma_f32 v0, -v0, v152, v3
	v_div_fmas_f32 v0, v0, v1, v152
	v_div_fixup_f32 v156, v0, v156, 1.0
	v_mul_f32_e32 v156, v156, v172
	v_div_scale_f32 v0, vcc, v157, v157, 1.0
	v_rcp_f32_e32 v1, v0
	s_nop 0
	v_fma_f32 v3, -v0, v1, 1.0
	v_fmac_f32_e32 v1, v3, v1
	v_div_scale_f32 v3, vcc, 1.0, v157, 1.0
	v_mul_f32_e32 v152, v3, v1
	v_fma_f32 v153, -v0, v152, v3
	v_fmac_f32_e32 v152, v153, v1
	v_fma_f32 v0, -v0, v152, v3
	v_div_fmas_f32 v0, v0, v1, v152
	v_div_fixup_f32 v157, v0, v157, 1.0
	v_mul_f32_e32 v157, v157, v173
	v_div_scale_f32 v0, vcc, v158, v158, 1.0
	v_rcp_f32_e32 v1, v0
	s_nop 0
	v_fma_f32 v3, -v0, v1, 1.0
	v_fmac_f32_e32 v1, v3, v1
	v_div_scale_f32 v3, vcc, 1.0, v158, 1.0
	v_mul_f32_e32 v152, v3, v1
	v_fma_f32 v153, -v0, v152, v3
	v_fmac_f32_e32 v152, v153, v1
	v_fma_f32 v0, -v0, v152, v3
	v_div_fmas_f32 v0, v0, v1, v152
	v_div_fixup_f32 v158, v0, v158, 1.0
	v_mul_f32_e32 v158, v158, v174
	v_div_scale_f32 v0, vcc, v159, v159, 1.0
	v_rcp_f32_e32 v1, v0
	s_nop 0
	v_fma_f32 v3, -v0, v1, 1.0
	v_fmac_f32_e32 v1, v3, v1
	v_div_scale_f32 v3, vcc, 1.0, v159, 1.0
	v_mul_f32_e32 v152, v3, v1
	v_fma_f32 v153, -v0, v152, v3
	v_fmac_f32_e32 v152, v153, v1
	v_fma_f32 v0, -v0, v152, v3
	v_div_fmas_f32 v0, v0, v1, v152
	v_div_fixup_f32 v159, v0, v159, 1.0
	v_mul_f32_e32 v159, v159, v175
	v_cvt_pk_bf16_f32 v176, v156, v157
	v_cvt_pk_bf16_f32 v177, v158, v159
	global_store_dwordx2 v197, v[176:177], s[56:57] sc0 sc1
	v_add_u32_e32 v197, 0x2000, v197
	s_waitcnt vmcnt(23)
	s_waitcnt lgkmcnt(2)
	v_add_f32_e32 v160, v160, v148
	v_add_f32_e32 v161, v161, v149
	v_add_f32_e32 v162, v162, v150
	v_add_f32_e32 v163, v163, v151
	v_mul_f32_e32 v160, 0xbfb8aa3b, v160
	v_mul_f32_e32 v161, 0xbfb8aa3b, v161
	v_mul_f32_e32 v162, 0xbfb8aa3b, v162
	v_mul_f32_e32 v163, 0xbfb8aa3b, v163
	v_exp_f32_e32 v160, v160
	v_exp_f32_e32 v161, v161
	v_exp_f32_e32 v162, v162
	v_exp_f32_e32 v163, v163
	v_lshlrev_b32_e32 v172, 16, v102
	v_and_b32_e32 v173, s28, v102
	v_lshlrev_b32_e32 v174, 16, v103
	v_and_b32_e32 v175, s28, v103
	v_add_f32_e32 v160, 1.0, v160
	v_add_f32_e32 v161, 1.0, v161
	v_add_f32_e32 v162, 1.0, v162
	v_add_f32_e32 v163, 1.0, v163
	v_div_scale_f32 v0, vcc, v160, v160, 1.0
	v_rcp_f32_e32 v1, v0
	s_nop 0
	v_fma_f32 v3, -v0, v1, 1.0
	v_fmac_f32_e32 v1, v3, v1
	v_div_scale_f32 v3, vcc, 1.0, v160, 1.0
	v_mul_f32_e32 v152, v3, v1
	v_fma_f32 v153, -v0, v152, v3
	v_fmac_f32_e32 v152, v153, v1
	v_fma_f32 v0, -v0, v152, v3
	v_div_fmas_f32 v0, v0, v1, v152
	v_div_fixup_f32 v160, v0, v160, 1.0
	v_mul_f32_e32 v160, v160, v172
	v_div_scale_f32 v0, vcc, v161, v161, 1.0
	v_rcp_f32_e32 v1, v0
	s_nop 0
	v_fma_f32 v3, -v0, v1, 1.0
	v_fmac_f32_e32 v1, v3, v1
	v_div_scale_f32 v3, vcc, 1.0, v161, 1.0
	v_mul_f32_e32 v152, v3, v1
	v_fma_f32 v153, -v0, v152, v3
	v_fmac_f32_e32 v152, v153, v1
	v_fma_f32 v0, -v0, v152, v3
	v_div_fmas_f32 v0, v0, v1, v152
	v_div_fixup_f32 v161, v0, v161, 1.0
	v_mul_f32_e32 v161, v161, v173
	v_div_scale_f32 v0, vcc, v162, v162, 1.0
	v_rcp_f32_e32 v1, v0
	s_nop 0
	v_fma_f32 v3, -v0, v1, 1.0
	v_fmac_f32_e32 v1, v3, v1
	v_div_scale_f32 v3, vcc, 1.0, v162, 1.0
	v_mul_f32_e32 v152, v3, v1
	v_fma_f32 v153, -v0, v152, v3
	v_fmac_f32_e32 v152, v153, v1
	v_fma_f32 v0, -v0, v152, v3
	v_div_fmas_f32 v0, v0, v1, v152
	v_div_fixup_f32 v162, v0, v162, 1.0
	v_mul_f32_e32 v162, v162, v174
	v_div_scale_f32 v0, vcc, v163, v163, 1.0
	v_rcp_f32_e32 v1, v0
	s_nop 0
	v_fma_f32 v3, -v0, v1, 1.0
	v_fmac_f32_e32 v1, v3, v1
	v_div_scale_f32 v3, vcc, 1.0, v163, 1.0
	v_mul_f32_e32 v152, v3, v1
	v_fma_f32 v153, -v0, v152, v3
	v_fmac_f32_e32 v152, v153, v1
	v_fma_f32 v0, -v0, v152, v3
	v_div_fmas_f32 v0, v0, v1, v152
	v_div_fixup_f32 v163, v0, v163, 1.0
	v_mul_f32_e32 v163, v163, v175
	v_cvt_pk_bf16_f32 v178, v160, v161
	v_cvt_pk_bf16_f32 v179, v162, v163
	global_store_dwordx2 v197, v[178:179], s[56:57] sc0 sc1
	v_add_u32_e32 v197, 0x2000, v197
	s_waitcnt vmcnt(23)
	s_waitcnt lgkmcnt(1)
	v_add_f32_e32 v164, v164, v148
	v_add_f32_e32 v165, v165, v149
	v_add_f32_e32 v166, v166, v150
	v_add_f32_e32 v167, v167, v151
	v_mul_f32_e32 v164, 0xbfb8aa3b, v164
	v_mul_f32_e32 v165, 0xbfb8aa3b, v165
	v_mul_f32_e32 v166, 0xbfb8aa3b, v166
	v_mul_f32_e32 v167, 0xbfb8aa3b, v167
	v_exp_f32_e32 v164, v164
	v_exp_f32_e32 v165, v165
	v_exp_f32_e32 v166, v166
	v_exp_f32_e32 v167, v167
	v_lshlrev_b32_e32 v172, 16, v104
	v_and_b32_e32 v173, s28, v104
	v_lshlrev_b32_e32 v174, 16, v105
	v_and_b32_e32 v175, s28, v105
	v_add_f32_e32 v164, 1.0, v164
	v_add_f32_e32 v165, 1.0, v165
	v_add_f32_e32 v166, 1.0, v166
	v_add_f32_e32 v167, 1.0, v167
	v_div_scale_f32 v0, vcc, v164, v164, 1.0
	v_rcp_f32_e32 v1, v0
	s_nop 0
	v_fma_f32 v3, -v0, v1, 1.0
	v_fmac_f32_e32 v1, v3, v1
	v_div_scale_f32 v3, vcc, 1.0, v164, 1.0
	v_mul_f32_e32 v152, v3, v1
	v_fma_f32 v153, -v0, v152, v3
	v_fmac_f32_e32 v152, v153, v1
	v_fma_f32 v0, -v0, v152, v3
	v_div_fmas_f32 v0, v0, v1, v152
	v_div_fixup_f32 v164, v0, v164, 1.0
	v_mul_f32_e32 v164, v164, v172
	v_div_scale_f32 v0, vcc, v165, v165, 1.0
	v_rcp_f32_e32 v1, v0
	s_nop 0
	v_fma_f32 v3, -v0, v1, 1.0
	v_fmac_f32_e32 v1, v3, v1
	v_div_scale_f32 v3, vcc, 1.0, v165, 1.0
	v_mul_f32_e32 v152, v3, v1
	v_fma_f32 v153, -v0, v152, v3
	v_fmac_f32_e32 v152, v153, v1
	v_fma_f32 v0, -v0, v152, v3
	v_div_fmas_f32 v0, v0, v1, v152
	v_div_fixup_f32 v165, v0, v165, 1.0
	v_mul_f32_e32 v165, v165, v173
	v_div_scale_f32 v0, vcc, v166, v166, 1.0
	v_rcp_f32_e32 v1, v0
	s_nop 0
	v_fma_f32 v3, -v0, v1, 1.0
	v_fmac_f32_e32 v1, v3, v1
	v_div_scale_f32 v3, vcc, 1.0, v166, 1.0
	v_mul_f32_e32 v152, v3, v1
	v_fma_f32 v153, -v0, v152, v3
	v_fmac_f32_e32 v152, v153, v1
	v_fma_f32 v0, -v0, v152, v3
	v_div_fmas_f32 v0, v0, v1, v152
	v_div_fixup_f32 v166, v0, v166, 1.0
	v_mul_f32_e32 v166, v166, v174
	v_div_scale_f32 v0, vcc, v167, v167, 1.0
	v_rcp_f32_e32 v1, v0
	s_nop 0
	v_fma_f32 v3, -v0, v1, 1.0
	v_fmac_f32_e32 v1, v3, v1
	v_div_scale_f32 v3, vcc, 1.0, v167, 1.0
	v_mul_f32_e32 v152, v3, v1
	v_fma_f32 v153, -v0, v152, v3
	v_fmac_f32_e32 v152, v153, v1
	v_fma_f32 v0, -v0, v152, v3
	v_div_fmas_f32 v0, v0, v1, v152
	v_div_fixup_f32 v167, v0, v167, 1.0
	v_mul_f32_e32 v167, v167, v175
	v_cvt_pk_bf16_f32 v176, v164, v165
	v_cvt_pk_bf16_f32 v177, v166, v167
	global_store_dwordx2 v197, v[176:177], s[56:57] sc0 sc1
	v_add_u32_e32 v197, 0x2000, v197
	s_waitcnt vmcnt(23)
	s_waitcnt lgkmcnt(0)
	v_add_f32_e32 v168, v168, v148
	v_add_f32_e32 v169, v169, v149
	v_add_f32_e32 v170, v170, v150
	v_add_f32_e32 v171, v171, v151
	v_mul_f32_e32 v168, 0xbfb8aa3b, v168
	v_mul_f32_e32 v169, 0xbfb8aa3b, v169
	v_mul_f32_e32 v170, 0xbfb8aa3b, v170
	v_mul_f32_e32 v171, 0xbfb8aa3b, v171
	v_exp_f32_e32 v168, v168
	v_exp_f32_e32 v169, v169
	v_exp_f32_e32 v170, v170
	v_exp_f32_e32 v171, v171
	v_lshlrev_b32_e32 v172, 16, v106
	v_and_b32_e32 v173, s28, v106
	v_lshlrev_b32_e32 v174, 16, v107
	v_and_b32_e32 v175, s28, v107
	v_add_f32_e32 v168, 1.0, v168
	v_add_f32_e32 v169, 1.0, v169
	v_add_f32_e32 v170, 1.0, v170
	v_add_f32_e32 v171, 1.0, v171
	v_div_scale_f32 v0, vcc, v168, v168, 1.0
	v_rcp_f32_e32 v1, v0
	s_nop 0
	v_fma_f32 v3, -v0, v1, 1.0
	v_fmac_f32_e32 v1, v3, v1
	v_div_scale_f32 v3, vcc, 1.0, v168, 1.0
	v_mul_f32_e32 v152, v3, v1
	v_fma_f32 v153, -v0, v152, v3
	v_fmac_f32_e32 v152, v153, v1
	v_fma_f32 v0, -v0, v152, v3
	v_div_fmas_f32 v0, v0, v1, v152
	v_div_fixup_f32 v168, v0, v168, 1.0
	v_mul_f32_e32 v168, v168, v172
	v_div_scale_f32 v0, vcc, v169, v169, 1.0
	v_rcp_f32_e32 v1, v0
	s_nop 0
	v_fma_f32 v3, -v0, v1, 1.0
	v_fmac_f32_e32 v1, v3, v1
	v_div_scale_f32 v3, vcc, 1.0, v169, 1.0
	v_mul_f32_e32 v152, v3, v1
	v_fma_f32 v153, -v0, v152, v3
	v_fmac_f32_e32 v152, v153, v1
	v_fma_f32 v0, -v0, v152, v3
	v_div_fmas_f32 v0, v0, v1, v152
	v_div_fixup_f32 v169, v0, v169, 1.0
	v_mul_f32_e32 v169, v169, v173
	v_div_scale_f32 v0, vcc, v170, v170, 1.0
	v_rcp_f32_e32 v1, v0
	s_nop 0
	v_fma_f32 v3, -v0, v1, 1.0
	v_fmac_f32_e32 v1, v3, v1
	v_div_scale_f32 v3, vcc, 1.0, v170, 1.0
	v_mul_f32_e32 v152, v3, v1
	v_fma_f32 v153, -v0, v152, v3
	v_fmac_f32_e32 v152, v153, v1
	v_fma_f32 v0, -v0, v152, v3
	v_div_fmas_f32 v0, v0, v1, v152
	v_div_fixup_f32 v170, v0, v170, 1.0
	v_mul_f32_e32 v170, v170, v174
	v_div_scale_f32 v0, vcc, v171, v171, 1.0
	v_rcp_f32_e32 v1, v0
	s_nop 0
	v_fma_f32 v3, -v0, v1, 1.0
	v_fmac_f32_e32 v1, v3, v1
	v_div_scale_f32 v3, vcc, 1.0, v171, 1.0
	v_mul_f32_e32 v152, v3, v1
	v_fma_f32 v153, -v0, v152, v3
	v_fmac_f32_e32 v152, v153, v1
	v_fma_f32 v0, -v0, v152, v3
	v_div_fmas_f32 v0, v0, v1, v152
	v_div_fixup_f32 v171, v0, v171, 1.0
	v_mul_f32_e32 v171, v171, v175
	v_cvt_pk_bf16_f32 v178, v168, v169
	v_cvt_pk_bf16_f32 v179, v170, v171
	global_store_dwordx2 v197, v[178:179], s[56:57] sc0 sc1
	v_add_u32_e32 v197, 0x2000, v197
	s_add_u32 s4, s4, 1
	s_cmp_eq_u32 s4, 6
	s_cbranch_scc1 .Lgm_glu_glu_done5
	s_waitcnt vmcnt(4)
	v_mov_b32_e32 v4, v20
	v_mov_b32_e32 v5, v21
	v_mov_b32_e32 v6, v22
	v_mov_b32_e32 v7, v23
	v_mov_b32_e32 v8, v24
	v_mov_b32_e32 v9, v25
	v_mov_b32_e32 v10, v26
	v_mov_b32_e32 v11, v27
	v_mov_b32_e32 v12, v28
	v_mov_b32_e32 v13, v29
	v_mov_b32_e32 v14, v30
	v_mov_b32_e32 v15, v31
	v_mov_b32_e32 v16, v32
	v_mov_b32_e32 v17, v33
	v_mov_b32_e32 v18, v34
	v_mov_b32_e32 v19, v35
	v_mov_b32_e32 v20, v36
	v_mov_b32_e32 v21, v37
	v_mov_b32_e32 v22, v38
	v_mov_b32_e32 v23, v39
	v_mov_b32_e32 v24, v40
	v_mov_b32_e32 v25, v41
	v_mov_b32_e32 v26, v42
	v_mov_b32_e32 v27, v43
	v_mov_b32_e32 v28, v44
	v_mov_b32_e32 v29, v45
	v_mov_b32_e32 v30, v46
	v_mov_b32_e32 v31, v47
	v_mov_b32_e32 v32, v48
	v_mov_b32_e32 v33, v49
	v_mov_b32_e32 v34, v50
	v_mov_b32_e32 v35, v51
	v_mov_b32_e32 v36, v52
	v_mov_b32_e32 v37, v53
	v_mov_b32_e32 v38, v54
	v_mov_b32_e32 v39, v55
	v_mov_b32_e32 v40, v56
	v_mov_b32_e32 v41, v57
	v_mov_b32_e32 v42, v58
	v_mov_b32_e32 v43, v59
	v_mov_b32_e32 v44, v60
	v_mov_b32_e32 v45, v61
	v_mov_b32_e32 v46, v62
	v_mov_b32_e32 v47, v63
	v_mov_b32_e32 v48, v64
	v_mov_b32_e32 v49, v65
	v_mov_b32_e32 v50, v66
	v_mov_b32_e32 v51, v67
	v_mov_b32_e32 v52, v68
	v_mov_b32_e32 v53, v69
	v_mov_b32_e32 v54, v70
	v_mov_b32_e32 v55, v71
	v_mov_b32_e32 v56, v72
	v_mov_b32_e32 v57, v73
	v_mov_b32_e32 v58, v74
	v_mov_b32_e32 v59, v75
	v_mov_b32_e32 v60, v76
	v_mov_b32_e32 v61, v77
	v_mov_b32_e32 v62, v78
	v_mov_b32_e32 v63, v79
	v_mov_b32_e32 v64, v80
	v_mov_b32_e32 v65, v81
	v_mov_b32_e32 v66, v82
	v_mov_b32_e32 v67, v83
	v_mov_b32_e32 v68, v84
	v_mov_b32_e32 v69, v85
	v_mov_b32_e32 v70, v86
	v_mov_b32_e32 v71, v87
	v_mov_b32_e32 v72, v88
	v_mov_b32_e32 v73, v89
	v_mov_b32_e32 v74, v90
	v_mov_b32_e32 v75, v91
	v_mov_b32_e32 v76, v92
	v_mov_b32_e32 v77, v93
	v_mov_b32_e32 v78, v94
	v_mov_b32_e32 v79, v95
	v_mov_b32_e32 v80, v96
	v_mov_b32_e32 v81, v97
	v_mov_b32_e32 v82, v98
	v_mov_b32_e32 v83, v99
	v_mov_b32_e32 v100, v108
	v_mov_b32_e32 v101, v109
	v_mov_b32_e32 v102, v110
	v_mov_b32_e32 v103, v111
	v_mov_b32_e32 v104, v112
	v_mov_b32_e32 v105, v113
	v_mov_b32_e32 v106, v114
	v_mov_b32_e32 v107, v115
	v_mov_b32_e32 v108, v116
	v_mov_b32_e32 v109, v117
	v_mov_b32_e32 v110, v118
	v_mov_b32_e32 v111, v119
	v_mov_b32_e32 v112, v120
	v_mov_b32_e32 v113, v121
	v_mov_b32_e32 v114, v122
	v_mov_b32_e32 v115, v123
	v_mov_b32_e32 v116, v124
	v_mov_b32_e32 v117, v125
	v_mov_b32_e32 v118, v126
	v_mov_b32_e32 v119, v127
	v_mov_b32_e32 v120, v128
	v_mov_b32_e32 v121, v129
	v_mov_b32_e32 v122, v130
	v_mov_b32_e32 v123, v131
	v_mov_b32_e32 v124, v132
	v_mov_b32_e32 v125, v133
	v_mov_b32_e32 v126, v134
	v_mov_b32_e32 v127, v135
	v_mov_b32_e32 v128, v136
	v_mov_b32_e32 v129, v137
	v_mov_b32_e32 v130, v138
	v_mov_b32_e32 v131, v139
	v_mov_b32_e32 v132, v140
	v_mov_b32_e32 v133, v141
	v_mov_b32_e32 v134, v142
	v_mov_b32_e32 v135, v143
	v_mov_b32_e32 v136, v144
	v_mov_b32_e32 v137, v145
	v_mov_b32_e32 v138, v146
	v_mov_b32_e32 v139, v147
	s_branch .Lgm_glu_glu_ep4
.Lgm_glu_glu_done5:
	v_mov_b32_e32 v4, 0
	v_mov_b32_e32 v5, 0
	v_mov_b32_e32 v6, 0
	v_mov_b32_e32 v7, 0
	v_mov_b32_e32 v8, 0
	v_mov_b32_e32 v9, 0
	v_mov_b32_e32 v10, 0
	v_mov_b32_e32 v11, 0
	v_mov_b32_e32 v12, 0
	v_mov_b32_e32 v13, 0
	v_mov_b32_e32 v14, 0
	v_mov_b32_e32 v15, 0
	v_mov_b32_e32 v16, 0
	v_mov_b32_e32 v17, 0
	v_mov_b32_e32 v18, 0
	v_mov_b32_e32 v19, 0
	v_mov_b32_e32 v20, 0
	v_mov_b32_e32 v21, 0
	v_mov_b32_e32 v22, 0
	v_mov_b32_e32 v23, 0
	v_mov_b32_e32 v24, 0
	v_mov_b32_e32 v25, 0
	v_mov_b32_e32 v26, 0
	v_mov_b32_e32 v27, 0
	v_mov_b32_e32 v28, 0
	v_mov_b32_e32 v29, 0
	v_mov_b32_e32 v30, 0
	v_mov_b32_e32 v31, 0
	v_mov_b32_e32 v32, 0
	v_mov_b32_e32 v33, 0
	v_mov_b32_e32 v34, 0
	v_mov_b32_e32 v35, 0
	v_mov_b32_e32 v36, 0
	v_mov_b32_e32 v37, 0
	v_mov_b32_e32 v38, 0
	v_mov_b32_e32 v39, 0
	v_mov_b32_e32 v40, 0
	v_mov_b32_e32 v41, 0
	v_mov_b32_e32 v42, 0
	v_mov_b32_e32 v43, 0
	v_mov_b32_e32 v44, 0
	v_mov_b32_e32 v45, 0
	v_mov_b32_e32 v46, 0
	v_mov_b32_e32 v47, 0
	v_mov_b32_e32 v48, 0
	v_mov_b32_e32 v49, 0
	v_mov_b32_e32 v50, 0
	v_mov_b32_e32 v51, 0
	v_mov_b32_e32 v52, 0
	v_mov_b32_e32 v53, 0
	v_mov_b32_e32 v54, 0
	v_mov_b32_e32 v55, 0
	v_mov_b32_e32 v56, 0
	v_mov_b32_e32 v57, 0
	v_mov_b32_e32 v58, 0
	v_mov_b32_e32 v59, 0
	v_mov_b32_e32 v60, 0
	v_mov_b32_e32 v61, 0
	v_mov_b32_e32 v62, 0
	v_mov_b32_e32 v63, 0
	v_mov_b32_e32 v64, 0
	v_mov_b32_e32 v65, 0
	v_mov_b32_e32 v66, 0
	v_mov_b32_e32 v67, 0
	v_mov_b32_e32 v68, 0
	v_mov_b32_e32 v69, 0
	v_mov_b32_e32 v70, 0
	v_mov_b32_e32 v71, 0
	v_mov_b32_e32 v72, 0
	v_mov_b32_e32 v73, 0
	v_mov_b32_e32 v74, 0
	v_mov_b32_e32 v75, 0
	v_mov_b32_e32 v76, 0
	v_mov_b32_e32 v77, 0
	v_mov_b32_e32 v78, 0
	v_mov_b32_e32 v79, 0
	v_mov_b32_e32 v80, 0
	v_mov_b32_e32 v81, 0
	v_mov_b32_e32 v82, 0
	v_mov_b32_e32 v83, 0
	v_mov_b32_e32 v84, 0
	v_mov_b32_e32 v85, 0
	v_mov_b32_e32 v86, 0
	v_mov_b32_e32 v87, 0
	v_mov_b32_e32 v88, 0
	v_mov_b32_e32 v89, 0
	v_mov_b32_e32 v90, 0
	v_mov_b32_e32 v91, 0
	v_mov_b32_e32 v92, 0
	v_mov_b32_e32 v93, 0
	v_mov_b32_e32 v94, 0
	v_mov_b32_e32 v95, 0
	v_mov_b32_e32 v96, 0
	v_mov_b32_e32 v97, 0
	v_mov_b32_e32 v98, 0
	v_mov_b32_e32 v99, 0
	s_mov_b32 s34, 0
	s_add_u32 s35, s35, s52
	s_cmp_ge_u32 s31, s30
	s_cbranch_scc1 .Lgm_glu_exit

.LBB0_619:
	s_andn2_b64 vcc, exec, s[38:39]
	s_cbranch_vccnz .LBB0_633
	s_cmpk_lt_u32 s35, 0x80
	s_cbranch_scc0 .Lch_ctx
	v_and_b32_e32 v165, 63, v206
	v_lshrrev_b32_e32 v166, 6, v206
	v_and_b32_e32 v0, 15, v165
	v_readfirstlane_b32 s40, v166
	v_lshrrev_b32_e32 v1, 4, v165
	s_lshr_b32 s38, s35, 2
	s_and_b32 s42, s35, 3
	s_mov_b32 s43, s40
	s_lshr_b32 s100, s38, 4
	s_lshl_b32 s101, s100, 3
	s_add_u32 s101, s101, 32
	s_bfe_u32 s41, s38, 0x30001
	s_and_b32 s39, s38, 1
	s_lshl_b32 s8, s100, 1
	s_add_u32 s8, s8, s36
	s_lshl_b32 s8, s8, 1
	s_add_u32 s8, s8, s39
	s_lshl_b32 s8, s8, 3
	s_add_u32 s8, s8, s41
	s_add_u32 s100, s101, 7
	s_cmp_eq_u32 s39, 0
	s_cselect_b32 s101, s101, s100
	s_cselect_b32 s92, 0, -1
	s_mov_b32 s98, 0xfffe0000
	s_cselect_b32 s98, 0x20000, s98
	s_mov_b32 s99, 0xffff0000
	s_cselect_b32 s99, 0x10000, s99
	s_mov_b32 s6, 0xfffc0000
	s_cselect_b32 s6, 0x40000, s6
	s_mov_b32 s7, 0xffffe000
	s_cselect_b32 s7, 0x2000, s7
	s_lshl_b32 s100, s101, 3
	s_add_u32 s100, s100, s41
	s_lshl_b32 s100, s100, 14
	s_lshl_b32 s9, s42, 12
	s_add_u32 s100, s100, s9
	s_add_u32 s100, s100, 0xc184000
	s_add_u32 s44, s96, s100
	s_addc_u32 s45, s97, 0
	s_lshl_b32 s100, s101, 1
	s_lshr_b32 s9, s41, 2
	s_add_u32 s100, s100, s9
	s_lshl_b32 s100, s100, 15
	s_lshl_b32 s9, s43, 12
	s_add_u32 s100, s100, s9
	s_add_u32 s100, s100, 0xbe84000
	s_add_u32 s46, s96, s100
	s_addc_u32 s47, s97, 0
	s_lshl_b32 s100, s101, 1
	s_add_u32 s100, s100, s39
	s_lshl_b32 s100, s100, 3
	s_add_u32 s100, s100, s41
	s_lshl_b32 s9, s100, 14
	s_lshl_b32 s59, s42, 12
	s_add_u32 s9, s9, s59
	s_lshl_b32 s59, s43, 5
	s_add_u32 s9, s9, s59
	s_add_u32 s9, s9, 0xac84000
	s_add_u32 s48, s96, s9
	s_addc_u32 s49, s97, 0
	s_lshl_b32 s100, s100, 9
	s_add_u32 s9, s100, 0xcae4000
	s_add_u32 s58, s96, s9
	s_addc_u32 s59, s97, 0
	s_cmp_eq_u32 s39, 0
	s_cselect_b32 s9, 0x1fc, 0
	s_add_u32 s58, s58, s9
	s_addc_u32 s59, s59, 0
	global_load_dword v171, v2, s[58:59]
	s_add_u32 s58, s58, s7
	s_addc_u32 s59, s59, s92
	global_load_dword v172, v2, s[58:59]
	s_add_u32 s58, s58, s7
	s_addc_u32 s59, s59, s92
	global_load_dword v173, v2, s[58:59]
	s_add_u32 s58, s58, s7
	s_addc_u32 s59, s59, s92
	global_load_dword v174, v2, s[58:59]
	s_add_u32 s58, s58, s7
	s_addc_u32 s59, s59, s92
	global_load_dword v175, v2, s[58:59]
	s_add_u32 s58, s58, s7
	s_addc_u32 s59, s59, s92
	global_load_dword v176, v2, s[58:59]
	s_add_u32 s58, s58, s7
	s_addc_u32 s59, s59, s92
	global_load_dword v177, v2, s[58:59]
	s_add_u32 s58, s58, s7
	s_addc_u32 s59, s59, s92
	global_load_dword v178, v2, s[58:59]
	s_add_u32 s9, s100, 0xcb44000
	s_add_u32 s58, s96, s9
	s_addc_u32 s59, s97, 0
	s_cmp_eq_u32 s39, 0
	s_cbranch_scc1 .Lch_lat_fw
	s_sub_u32 s58, s58, 0x2000
	s_subb_u32 s59, s59, 0
.Lch_lat_fw:
	v_lshrrev_b32_e32 v167, 5, v165
	v_and_b32_e32 v168, 31, v165
	v_lshlrev_b32_e32 v167, 13, v167
	v_lshl_add_u32 v167, v168, 4, v167
	s_lshl_b32 s9, s40, 12
	s_lshl_b32 s100, s7, 1
	s_add_u32 m0, s9, 0x0
	s_nop 0
	global_load_lds_dwordx4 v167, s[58:59]
	s_add_u32 s58, s58, s100
	s_addc_u32 s59, s59, s92
	s_add_u32 m0, s9, 0x400
	s_nop 0
	global_load_lds_dwordx4 v167, s[58:59]
	s_add_u32 s58, s58, s100
	s_addc_u32 s59, s59, s92
	s_add_u32 m0, s9, 0x800
	s_nop 0
	global_load_lds_dwordx4 v167, s[58:59]
	s_add_u32 s58, s58, s100
	s_addc_u32 s59, s59, s92
	s_add_u32 m0, s9, 0xc00
	s_nop 0
	global_load_lds_dwordx4 v167, s[58:59]
	v_lshlrev_b32_e32 v160, 8, v0
	v_lshl_add_u32 v160, v1, 4, v160
	v_lshlrev_b32_e32 v161, 11, v1
	v_lshl_add_u32 v161, v0, 2, v161
	v_lshrrev_b32_e32 v162, 1, v161
	v_lshl_add_u32 v163, v1, 5, s9
	s_lshl_b32 s100, s8, 15
	s_lshl_b32 s9, s42, 13
	s_add_u32 s100, s100, s9
	s_lshl_b32 s9, s43, 6
	s_add_u32 s100, s100, s9
	s_add_u32 s58, s72, s100
	s_addc_u32 s59, s73, 0
	global_load_dword v156, v161, s[58:59]
	global_load_dword v157, v161, s[58:59] offset:512
	global_load_dword v158, v161, s[58:59] offset:1024
	global_load_dword v159, v161, s[58:59] offset:1536
	global_load_dwordx4 v[4:7], v160, s[44:45]
	global_load_dwordx4 v[8:11], v160, s[44:45] offset:64
	global_load_dwordx4 v[12:15], v160, s[44:45] offset:128
	global_load_dwordx4 v[16:19], v160, s[44:45] offset:192
	global_load_dwordx4 v[20:23], v160, s[46:47]
	global_load_dwordx4 v[24:27], v160, s[46:47] offset:64
	global_load_dwordx4 v[28:31], v160, s[46:47] offset:128
	global_load_dwordx4 v[32:35], v160, s[46:47] offset:192
	s_add_u32 s44, s44, s98
	s_addc_u32 s45, s45, s92
	s_add_u32 s46, s46, s99
	s_addc_u32 s47, s47, s92
	global_load_dwordx4 v[36:39], v160, s[44:45]
	global_load_dwordx4 v[40:43], v160, s[44:45] offset:64
	global_load_dwordx4 v[44:47], v160, s[44:45] offset:128
	global_load_dwordx4 v[48:51], v160, s[44:45] offset:192
	global_load_dwordx4 v[52:55], v160, s[46:47]
	global_load_dwordx4 v[56:59], v160, s[46:47] offset:64
	global_load_dwordx4 v[60:63], v160, s[46:47] offset:128
	global_load_dwordx4 v[64:67], v160, s[46:47] offset:192
	s_add_u32 s44, s44, s98
	s_addc_u32 s45, s45, s92
	s_add_u32 s46, s46, s99
	s_addc_u32 s47, s47, s92
	global_load_dwordx4 v[68:71], v160, s[44:45]
	global_load_dwordx4 v[72:75], v160, s[44:45] offset:64
	global_load_dwordx4 v[76:79], v160, s[44:45] offset:128
	global_load_dwordx4 v[80:83], v160, s[44:45] offset:192
	global_load_dwordx4 v[84:87], v160, s[46:47]
	global_load_dwordx4 v[88:91], v160, s[46:47] offset:64
	global_load_dwordx4 v[92:95], v160, s[46:47] offset:128
	global_load_dwordx4 v[96:99], v160, s[46:47] offset:192
	s_add_u32 s44, s44, s98
	s_addc_u32 s45, s45, s92
	s_add_u32 s46, s46, s99
	s_addc_u32 s47, s47, s92
	global_load_dwordx4 v[100:103], v160, s[44:45]
	global_load_dwordx4 v[104:107], v160, s[44:45] offset:64
	global_load_dwordx4 v[108:111], v160, s[44:45] offset:128
	global_load_dwordx4 v[112:115], v160, s[44:45] offset:192
	global_load_dwordx4 v[116:119], v160, s[46:47]
	global_load_dwordx4 v[120:123], v160, s[46:47] offset:64
	global_load_dwordx4 v[124:127], v160, s[46:47] offset:128
	global_load_dwordx4 v[128:131], v160, s[46:47] offset:192
	s_add_u32 s44, s44, s98
	s_addc_u32 s45, s45, s92
	s_add_u32 s46, s46, s99
	s_addc_u32 s47, s47, s92
	s_waitcnt vmcnt(24)
	s_xor_b32 s100, s39, 0
	s_lshl_b32 s100, s100, 9
	v_add_u32_e32 v170, s100, v163
	s_nop 0
	ds_read_b128 v[132:135], v170
	ds_read_b128 v[136:139], v170 offset:16
	v_bfe_u32 v165, v156, 16, 1
	v_add3_u32 v165, v156, v165, s27
	global_store_short_d16_hi v162, v165, s[48:49] offset:0
	v_bfe_u32 v166, v157, 16, 1
	v_add3_u32 v166, v157, v166, s27
	global_store_short_d16_hi v162, v166, s[48:49] offset:256
	v_bfe_u32 v167, v158, 16, 1
	v_add3_u32 v167, v158, v167, s27
	global_store_short_d16_hi v162, v167, s[48:49] offset:512
	v_bfe_u32 v168, v159, 16, 1
	v_add3_u32 v168, v159, v168, s27
	global_store_short_d16_hi v162, v168, s[48:49] offset:768
	s_add_u32 s48, s48, s6
	s_addc_u32 s49, s49, s92
	v_mul_f32_e32 v164, 0x3fb8aa3b, v171
	v_exp_f32_e32 v164, v164
	s_nop 0
	v_mul_f32_e32 v156, v156, v164
	v_mul_f32_e32 v157, v157, v164
	v_mul_f32_e32 v158, v158, v164
	v_mul_f32_e32 v159, v159, v164
	ds_read_b128 v[140:143], v170 offset:128
	ds_read_b128 v[144:147], v170 offset:144
	s_waitcnt lgkmcnt(2)
	v_lshlrev_b32_e32 v165, 16, v4
	v_and_b32_e32 v166, s28, v4
	v_mul_f32_e32 v165, v165, v132
	v_mul_f32_e32 v166, v166, v133
	v_cvt_pk_bf16_f32 v148, v165, v166
	v_lshlrev_b32_e32 v165, 16, v5
	v_and_b32_e32 v166, s28, v5
	v_mul_f32_e32 v165, v165, v134
	v_mul_f32_e32 v166, v166, v135
	v_cvt_pk_bf16_f32 v149, v165, v166
	v_lshlrev_b32_e32 v165, 16, v6
	v_and_b32_e32 v166, s28, v6
	v_mul_f32_e32 v165, v165, v136
	v_mul_f32_e32 v166, v166, v137
	v_cvt_pk_bf16_f32 v150, v165, v166
	v_lshlrev_b32_e32 v165, 16, v7
	v_and_b32_e32 v166, s28, v7
	v_mul_f32_e32 v165, v165, v138
	v_mul_f32_e32 v166, v166, v139
	v_cvt_pk_bf16_f32 v151, v165, v166
	s_nop 1
	v_mfma_f32_16x16x32_bf16 v[156:159], v[148:151], v[20:23], v[156:159]
	ds_read_b128 v[132:135], v170 offset:256
	ds_read_b128 v[136:139], v170 offset:272
	s_waitcnt lgkmcnt(2)
	v_lshlrev_b32_e32 v165, 16, v8
	v_and_b32_e32 v166, s28, v8
	v_mul_f32_e32 v165, v165, v140
	v_mul_f32_e32 v166, v166, v141
	v_cvt_pk_bf16_f32 v152, v165, v166
	v_lshlrev_b32_e32 v165, 16, v9
	v_and_b32_e32 v166, s28, v9
	v_mul_f32_e32 v165, v165, v142
	v_mul_f32_e32 v166, v166, v143
	v_cvt_pk_bf16_f32 v153, v165, v166
	v_lshlrev_b32_e32 v165, 16, v10
	v_and_b32_e32 v166, s28, v10
	v_mul_f32_e32 v165, v165, v144
	v_mul_f32_e32 v166, v166, v145
	v_cvt_pk_bf16_f32 v154, v165, v166
	v_lshlrev_b32_e32 v165, 16, v11
	v_and_b32_e32 v166, s28, v11
	v_mul_f32_e32 v165, v165, v146
	v_mul_f32_e32 v166, v166, v147
	v_cvt_pk_bf16_f32 v155, v165, v166
	s_nop 1
	v_mfma_f32_16x16x32_bf16 v[156:159], v[152:155], v[24:27], v[156:159]
	ds_read_b128 v[140:143], v170 offset:384
	ds_read_b128 v[144:147], v170 offset:400
	s_waitcnt lgkmcnt(2)
	v_lshlrev_b32_e32 v165, 16, v12
	v_and_b32_e32 v166, s28, v12
	v_mul_f32_e32 v165, v165, v132
	v_mul_f32_e32 v166, v166, v133
	v_cvt_pk_bf16_f32 v148, v165, v166
	v_lshlrev_b32_e32 v165, 16, v13
	v_and_b32_e32 v166, s28, v13
	v_mul_f32_e32 v165, v165, v134
	v_mul_f32_e32 v166, v166, v135
	v_cvt_pk_bf16_f32 v149, v165, v166
	v_lshlrev_b32_e32 v165, 16, v14
	v_and_b32_e32 v166, s28, v14
	v_mul_f32_e32 v165, v165, v136
	v_mul_f32_e32 v166, v166, v137
	v_cvt_pk_bf16_f32 v150, v165, v166
	v_lshlrev_b32_e32 v165, 16, v15
	v_and_b32_e32 v166, s28, v15
	v_mul_f32_e32 v165, v165, v138
	v_mul_f32_e32 v166, v166, v139
	v_cvt_pk_bf16_f32 v151, v165, v166
	s_nop 1
	v_mfma_f32_16x16x32_bf16 v[156:159], v[148:151], v[28:31], v[156:159]
	s_waitcnt lgkmcnt(0)
	v_lshlrev_b32_e32 v165, 16, v16
	v_and_b32_e32 v166, s28, v16
	v_mul_f32_e32 v165, v165, v140
	v_mul_f32_e32 v166, v166, v141
	v_cvt_pk_bf16_f32 v152, v165, v166
	v_lshlrev_b32_e32 v165, 16, v17
	v_and_b32_e32 v166, s28, v17
	v_mul_f32_e32 v165, v165, v142
	v_mul_f32_e32 v166, v166, v143
	v_cvt_pk_bf16_f32 v153, v165, v166
	v_lshlrev_b32_e32 v165, 16, v18
	v_and_b32_e32 v166, s28, v18
	v_mul_f32_e32 v165, v165, v144
	v_mul_f32_e32 v166, v166, v145
	v_cvt_pk_bf16_f32 v154, v165, v166
	v_lshlrev_b32_e32 v165, 16, v19
	v_and_b32_e32 v166, s28, v19
	v_mul_f32_e32 v165, v165, v146
	v_mul_f32_e32 v166, v166, v147
	v_cvt_pk_bf16_f32 v155, v165, v166
	s_nop 1
	v_mfma_f32_16x16x32_bf16 v[156:159], v[152:155], v[32:35], v[156:159]
	global_load_dwordx4 v[4:7], v160, s[44:45]
	global_load_dwordx4 v[8:11], v160, s[44:45] offset:64
	global_load_dwordx4 v[12:15], v160, s[44:45] offset:128
	global_load_dwordx4 v[16:19], v160, s[44:45] offset:192
	global_load_dwordx4 v[20:23], v160, s[46:47]
	global_load_dwordx4 v[24:27], v160, s[46:47] offset:64
	global_load_dwordx4 v[28:31], v160, s[46:47] offset:128
	global_load_dwordx4 v[32:35], v160, s[46:47] offset:192
	s_add_u32 s44, s44, s98
	s_addc_u32 s45, s45, s92
	s_add_u32 s46, s46, s99
	s_addc_u32 s47, s47, s92
	s_waitcnt vmcnt(28)
	s_xor_b32 s100, s39, 1
	s_lshl_b32 s100, s100, 9
	v_add_u32_e32 v170, s100, v163
	s_nop 0
	ds_read_b128 v[132:135], v170
	ds_read_b128 v[136:139], v170 offset:16
	v_bfe_u32 v165, v156, 16, 1
	v_add3_u32 v165, v156, v165, s27
	global_store_short_d16_hi v162, v165, s[48:49] offset:0
	v_bfe_u32 v166, v157, 16, 1
	v_add3_u32 v166, v157, v166, s27
	global_store_short_d16_hi v162, v166, s[48:49] offset:256
	v_bfe_u32 v167, v158, 16, 1
	v_add3_u32 v167, v158, v167, s27
	global_store_short_d16_hi v162, v167, s[48:49] offset:512
	v_bfe_u32 v168, v159, 16, 1
	v_add3_u32 v168, v159, v168, s27
	global_store_short_d16_hi v162, v168, s[48:49] offset:768
	s_add_u32 s48, s48, s6
	s_addc_u32 s49, s49, s92
	v_mul_f32_e32 v164, 0x3fb8aa3b, v172
	v_exp_f32_e32 v164, v164
	s_nop 0
	v_mul_f32_e32 v156, v156, v164
	v_mul_f32_e32 v157, v157, v164
	v_mul_f32_e32 v158, v158, v164
	v_mul_f32_e32 v159, v159, v164
	ds_read_b128 v[140:143], v170 offset:128
	ds_read_b128 v[144:147], v170 offset:144
	s_waitcnt lgkmcnt(2)
	v_lshlrev_b32_e32 v165, 16, v36
	v_and_b32_e32 v166, s28, v36
	v_mul_f32_e32 v165, v165, v132
	v_mul_f32_e32 v166, v166, v133
	v_cvt_pk_bf16_f32 v148, v165, v166
	v_lshlrev_b32_e32 v165, 16, v37
	v_and_b32_e32 v166, s28, v37
	v_mul_f32_e32 v165, v165, v134
	v_mul_f32_e32 v166, v166, v135
	v_cvt_pk_bf16_f32 v149, v165, v166
	v_lshlrev_b32_e32 v165, 16, v38
	v_and_b32_e32 v166, s28, v38
	v_mul_f32_e32 v165, v165, v136
	v_mul_f32_e32 v166, v166, v137
	v_cvt_pk_bf16_f32 v150, v165, v166
	v_lshlrev_b32_e32 v165, 16, v39
	v_and_b32_e32 v166, s28, v39
	v_mul_f32_e32 v165, v165, v138
	v_mul_f32_e32 v166, v166, v139
	v_cvt_pk_bf16_f32 v151, v165, v166
	s_nop 1
	v_mfma_f32_16x16x32_bf16 v[156:159], v[148:151], v[52:55], v[156:159]
	ds_read_b128 v[132:135], v170 offset:256
	ds_read_b128 v[136:139], v170 offset:272
	s_waitcnt lgkmcnt(2)
	v_lshlrev_b32_e32 v165, 16, v40
	v_and_b32_e32 v166, s28, v40
	v_mul_f32_e32 v165, v165, v140
	v_mul_f32_e32 v166, v166, v141
	v_cvt_pk_bf16_f32 v152, v165, v166
	v_lshlrev_b32_e32 v165, 16, v41
	v_and_b32_e32 v166, s28, v41
	v_mul_f32_e32 v165, v165, v142
	v_mul_f32_e32 v166, v166, v143
	v_cvt_pk_bf16_f32 v153, v165, v166
	v_lshlrev_b32_e32 v165, 16, v42
	v_and_b32_e32 v166, s28, v42
	v_mul_f32_e32 v165, v165, v144
	v_mul_f32_e32 v166, v166, v145
	v_cvt_pk_bf16_f32 v154, v165, v166
	v_lshlrev_b32_e32 v165, 16, v43
	v_and_b32_e32 v166, s28, v43
	v_mul_f32_e32 v165, v165, v146
	v_mul_f32_e32 v166, v166, v147
	v_cvt_pk_bf16_f32 v155, v165, v166
	s_nop 1
	v_mfma_f32_16x16x32_bf16 v[156:159], v[152:155], v[56:59], v[156:159]
	ds_read_b128 v[140:143], v170 offset:384
	ds_read_b128 v[144:147], v170 offset:400
	s_waitcnt lgkmcnt(2)
	v_lshlrev_b32_e32 v165, 16, v44
	v_and_b32_e32 v166, s28, v44
	v_mul_f32_e32 v165, v165, v132
	v_mul_f32_e32 v166, v166, v133
	v_cvt_pk_bf16_f32 v148, v165, v166
	v_lshlrev_b32_e32 v165, 16, v45
	v_and_b32_e32 v166, s28, v45
	v_mul_f32_e32 v165, v165, v134
	v_mul_f32_e32 v166, v166, v135
	v_cvt_pk_bf16_f32 v149, v165, v166
	v_lshlrev_b32_e32 v165, 16, v46
	v_and_b32_e32 v166, s28, v46
	v_mul_f32_e32 v165, v165, v136
	v_mul_f32_e32 v166, v166, v137
	v_cvt_pk_bf16_f32 v150, v165, v166
	v_lshlrev_b32_e32 v165, 16, v47
	v_and_b32_e32 v166, s28, v47
	v_mul_f32_e32 v165, v165, v138
	v_mul_f32_e32 v166, v166, v139
	v_cvt_pk_bf16_f32 v151, v165, v166
	s_nop 1
	v_mfma_f32_16x16x32_bf16 v[156:159], v[148:151], v[60:63], v[156:159]
	s_waitcnt lgkmcnt(0)
	v_lshlrev_b32_e32 v165, 16, v48
	v_and_b32_e32 v166, s28, v48
	v_mul_f32_e32 v165, v165, v140
	v_mul_f32_e32 v166, v166, v141
	v_cvt_pk_bf16_f32 v152, v165, v166
	v_lshlrev_b32_e32 v165, 16, v49
	v_and_b32_e32 v166, s28, v49
	v_mul_f32_e32 v165, v165, v142
	v_mul_f32_e32 v166, v166, v143
	v_cvt_pk_bf16_f32 v153, v165, v166
	v_lshlrev_b32_e32 v165, 16, v50
	v_and_b32_e32 v166, s28, v50
	v_mul_f32_e32 v165, v165, v144
	v_mul_f32_e32 v166, v166, v145
	v_cvt_pk_bf16_f32 v154, v165, v166
	v_lshlrev_b32_e32 v165, 16, v51
	v_and_b32_e32 v166, s28, v51
	v_mul_f32_e32 v165, v165, v146
	v_mul_f32_e32 v166, v166, v147
	v_cvt_pk_bf16_f32 v155, v165, v166
	s_nop 1
	v_mfma_f32_16x16x32_bf16 v[156:159], v[152:155], v[64:67], v[156:159]
	global_load_dwordx4 v[36:39], v160, s[44:45]
	global_load_dwordx4 v[40:43], v160, s[44:45] offset:64
	global_load_dwordx4 v[44:47], v160, s[44:45] offset:128
	global_load_dwordx4 v[48:51], v160, s[44:45] offset:192
	global_load_dwordx4 v[52:55], v160, s[46:47]
	global_load_dwordx4 v[56:59], v160, s[46:47] offset:64
	global_load_dwordx4 v[60:63], v160, s[46:47] offset:128
	global_load_dwordx4 v[64:67], v160, s[46:47] offset:192
	s_add_u32 s44, s44, s98
	s_addc_u32 s45, s45, s92
	s_add_u32 s46, s46, s99
	s_addc_u32 s47, s47, s92
	s_waitcnt vmcnt(32)
	s_xor_b32 s100, s39, 2
	s_lshl_b32 s100, s100, 9
	v_add_u32_e32 v170, s100, v163
	s_nop 0
	ds_read_b128 v[132:135], v170
	ds_read_b128 v[136:139], v170 offset:16
	v_bfe_u32 v165, v156, 16, 1
	v_add3_u32 v165, v156, v165, s27
	global_store_short_d16_hi v162, v165, s[48:49] offset:0
	v_bfe_u32 v166, v157, 16, 1
	v_add3_u32 v166, v157, v166, s27
	global_store_short_d16_hi v162, v166, s[48:49] offset:256
	v_bfe_u32 v167, v158, 16, 1
	v_add3_u32 v167, v158, v167, s27
	global_store_short_d16_hi v162, v167, s[48:49] offset:512
	v_bfe_u32 v168, v159, 16, 1
	v_add3_u32 v168, v159, v168, s27
	global_store_short_d16_hi v162, v168, s[48:49] offset:768
	s_add_u32 s48, s48, s6
	s_addc_u32 s49, s49, s92
	v_mul_f32_e32 v164, 0x3fb8aa3b, v173
	v_exp_f32_e32 v164, v164
	s_nop 0
	v_mul_f32_e32 v156, v156, v164
	v_mul_f32_e32 v157, v157, v164
	v_mul_f32_e32 v158, v158, v164
	v_mul_f32_e32 v159, v159, v164
	ds_read_b128 v[140:143], v170 offset:128
	ds_read_b128 v[144:147], v170 offset:144
	s_waitcnt lgkmcnt(2)
	v_lshlrev_b32_e32 v165, 16, v68
	v_and_b32_e32 v166, s28, v68
	v_mul_f32_e32 v165, v165, v132
	v_mul_f32_e32 v166, v166, v133
	v_cvt_pk_bf16_f32 v148, v165, v166
	v_lshlrev_b32_e32 v165, 16, v69
	v_and_b32_e32 v166, s28, v69
	v_mul_f32_e32 v165, v165, v134
	v_mul_f32_e32 v166, v166, v135
	v_cvt_pk_bf16_f32 v149, v165, v166
	v_lshlrev_b32_e32 v165, 16, v70
	v_and_b32_e32 v166, s28, v70
	v_mul_f32_e32 v165, v165, v136
	v_mul_f32_e32 v166, v166, v137
	v_cvt_pk_bf16_f32 v150, v165, v166
	v_lshlrev_b32_e32 v165, 16, v71
	v_and_b32_e32 v166, s28, v71
	v_mul_f32_e32 v165, v165, v138
	v_mul_f32_e32 v166, v166, v139
	v_cvt_pk_bf16_f32 v151, v165, v166
	s_nop 1
	v_mfma_f32_16x16x32_bf16 v[156:159], v[148:151], v[84:87], v[156:159]
	ds_read_b128 v[132:135], v170 offset:256
	ds_read_b128 v[136:139], v170 offset:272
	s_waitcnt lgkmcnt(2)
	v_lshlrev_b32_e32 v165, 16, v72
	v_and_b32_e32 v166, s28, v72
	v_mul_f32_e32 v165, v165, v140
	v_mul_f32_e32 v166, v166, v141
	v_cvt_pk_bf16_f32 v152, v165, v166
	v_lshlrev_b32_e32 v165, 16, v73
	v_and_b32_e32 v166, s28, v73
	v_mul_f32_e32 v165, v165, v142
	v_mul_f32_e32 v166, v166, v143
	v_cvt_pk_bf16_f32 v153, v165, v166
	v_lshlrev_b32_e32 v165, 16, v74
	v_and_b32_e32 v166, s28, v74
	v_mul_f32_e32 v165, v165, v144
	v_mul_f32_e32 v166, v166, v145
	v_cvt_pk_bf16_f32 v154, v165, v166
	v_lshlrev_b32_e32 v165, 16, v75
	v_and_b32_e32 v166, s28, v75
	v_mul_f32_e32 v165, v165, v146
	v_mul_f32_e32 v166, v166, v147
	v_cvt_pk_bf16_f32 v155, v165, v166
	s_nop 1
	v_mfma_f32_16x16x32_bf16 v[156:159], v[152:155], v[88:91], v[156:159]
	ds_read_b128 v[140:143], v170 offset:384
	ds_read_b128 v[144:147], v170 offset:400
	s_waitcnt lgkmcnt(2)
	v_lshlrev_b32_e32 v165, 16, v76
	v_and_b32_e32 v166, s28, v76
	v_mul_f32_e32 v165, v165, v132
	v_mul_f32_e32 v166, v166, v133
	v_cvt_pk_bf16_f32 v148, v165, v166
	v_lshlrev_b32_e32 v165, 16, v77
	v_and_b32_e32 v166, s28, v77
	v_mul_f32_e32 v165, v165, v134
	v_mul_f32_e32 v166, v166, v135
	v_cvt_pk_bf16_f32 v149, v165, v166
	v_lshlrev_b32_e32 v165, 16, v78
	v_and_b32_e32 v166, s28, v78
	v_mul_f32_e32 v165, v165, v136
	v_mul_f32_e32 v166, v166, v137
	v_cvt_pk_bf16_f32 v150, v165, v166
	v_lshlrev_b32_e32 v165, 16, v79
	v_and_b32_e32 v166, s28, v79
	v_mul_f32_e32 v165, v165, v138
	v_mul_f32_e32 v166, v166, v139
	v_cvt_pk_bf16_f32 v151, v165, v166
	s_nop 1
	v_mfma_f32_16x16x32_bf16 v[156:159], v[148:151], v[92:95], v[156:159]
	s_waitcnt lgkmcnt(0)
	v_lshlrev_b32_e32 v165, 16, v80
	v_and_b32_e32 v166, s28, v80
	v_mul_f32_e32 v165, v165, v140
	v_mul_f32_e32 v166, v166, v141
	v_cvt_pk_bf16_f32 v152, v165, v166
	v_lshlrev_b32_e32 v165, 16, v81
	v_and_b32_e32 v166, s28, v81
	v_mul_f32_e32 v165, v165, v142
	v_mul_f32_e32 v166, v166, v143
	v_cvt_pk_bf16_f32 v153, v165, v166
	v_lshlrev_b32_e32 v165, 16, v82
	v_and_b32_e32 v166, s28, v82
	v_mul_f32_e32 v165, v165, v144
	v_mul_f32_e32 v166, v166, v145
	v_cvt_pk_bf16_f32 v154, v165, v166
	v_lshlrev_b32_e32 v165, 16, v83
	v_and_b32_e32 v166, s28, v83
	v_mul_f32_e32 v165, v165, v146
	v_mul_f32_e32 v166, v166, v147
	v_cvt_pk_bf16_f32 v155, v165, v166
	s_nop 1
	v_mfma_f32_16x16x32_bf16 v[156:159], v[152:155], v[96:99], v[156:159]
	global_load_dwordx4 v[68:71], v160, s[44:45]
	global_load_dwordx4 v[72:75], v160, s[44:45] offset:64
	global_load_dwordx4 v[76:79], v160, s[44:45] offset:128
	global_load_dwordx4 v[80:83], v160, s[44:45] offset:192
	global_load_dwordx4 v[84:87], v160, s[46:47]
	global_load_dwordx4 v[88:91], v160, s[46:47] offset:64
	global_load_dwordx4 v[92:95], v160, s[46:47] offset:128
	global_load_dwordx4 v[96:99], v160, s[46:47] offset:192
	s_add_u32 s44, s44, s98
	s_addc_u32 s45, s45, s92
	s_add_u32 s46, s46, s99
	s_addc_u32 s47, s47, s92
	s_waitcnt vmcnt(36)
	s_xor_b32 s100, s39, 3
	s_lshl_b32 s100, s100, 9
	v_add_u32_e32 v170, s100, v163
	s_nop 0
	ds_read_b128 v[132:135], v170
	ds_read_b128 v[136:139], v170 offset:16
	v_bfe_u32 v165, v156, 16, 1
	v_add3_u32 v165, v156, v165, s27
	global_store_short_d16_hi v162, v165, s[48:49] offset:0
	v_bfe_u32 v166, v157, 16, 1
	v_add3_u32 v166, v157, v166, s27
	global_store_short_d16_hi v162, v166, s[48:49] offset:256
	v_bfe_u32 v167, v158, 16, 1
	v_add3_u32 v167, v158, v167, s27
	global_store_short_d16_hi v162, v167, s[48:49] offset:512
	v_bfe_u32 v168, v159, 16, 1
	v_add3_u32 v168, v159, v168, s27
	global_store_short_d16_hi v162, v168, s[48:49] offset:768
	s_add_u32 s48, s48, s6
	s_addc_u32 s49, s49, s92
	v_mul_f32_e32 v164, 0x3fb8aa3b, v174
	v_exp_f32_e32 v164, v164
	s_nop 0
	v_mul_f32_e32 v156, v156, v164
	v_mul_f32_e32 v157, v157, v164
	v_mul_f32_e32 v158, v158, v164
	v_mul_f32_e32 v159, v159, v164
	ds_read_b128 v[140:143], v170 offset:128
	ds_read_b128 v[144:147], v170 offset:144
	s_waitcnt lgkmcnt(2)
	v_lshlrev_b32_e32 v165, 16, v100
	v_and_b32_e32 v166, s28, v100
	v_mul_f32_e32 v165, v165, v132
	v_mul_f32_e32 v166, v166, v133
	v_cvt_pk_bf16_f32 v148, v165, v166
	v_lshlrev_b32_e32 v165, 16, v101
	v_and_b32_e32 v166, s28, v101
	v_mul_f32_e32 v165, v165, v134
	v_mul_f32_e32 v166, v166, v135
	v_cvt_pk_bf16_f32 v149, v165, v166
	v_lshlrev_b32_e32 v165, 16, v102
	v_and_b32_e32 v166, s28, v102
	v_mul_f32_e32 v165, v165, v136
	v_mul_f32_e32 v166, v166, v137
	v_cvt_pk_bf16_f32 v150, v165, v166
	v_lshlrev_b32_e32 v165, 16, v103
	v_and_b32_e32 v166, s28, v103
	v_mul_f32_e32 v165, v165, v138
	v_mul_f32_e32 v166, v166, v139
	v_cvt_pk_bf16_f32 v151, v165, v166
	s_nop 1
	v_mfma_f32_16x16x32_bf16 v[156:159], v[148:151], v[116:119], v[156:159]
	ds_read_b128 v[132:135], v170 offset:256
	ds_read_b128 v[136:139], v170 offset:272
	s_waitcnt lgkmcnt(2)
	v_lshlrev_b32_e32 v165, 16, v104
	v_and_b32_e32 v166, s28, v104
	v_mul_f32_e32 v165, v165, v140
	v_mul_f32_e32 v166, v166, v141
	v_cvt_pk_bf16_f32 v152, v165, v166
	v_lshlrev_b32_e32 v165, 16, v105
	v_and_b32_e32 v166, s28, v105
	v_mul_f32_e32 v165, v165, v142
	v_mul_f32_e32 v166, v166, v143
	v_cvt_pk_bf16_f32 v153, v165, v166
	v_lshlrev_b32_e32 v165, 16, v106
	v_and_b32_e32 v166, s28, v106
	v_mul_f32_e32 v165, v165, v144
	v_mul_f32_e32 v166, v166, v145
	v_cvt_pk_bf16_f32 v154, v165, v166
	v_lshlrev_b32_e32 v165, 16, v107
	v_and_b32_e32 v166, s28, v107
	v_mul_f32_e32 v165, v165, v146
	v_mul_f32_e32 v166, v166, v147
	v_cvt_pk_bf16_f32 v155, v165, v166
	s_nop 1
	v_mfma_f32_16x16x32_bf16 v[156:159], v[152:155], v[120:123], v[156:159]
	ds_read_b128 v[140:143], v170 offset:384
	ds_read_b128 v[144:147], v170 offset:400
	s_waitcnt lgkmcnt(2)
	v_lshlrev_b32_e32 v165, 16, v108
	v_and_b32_e32 v166, s28, v108
	v_mul_f32_e32 v165, v165, v132
	v_mul_f32_e32 v166, v166, v133
	v_cvt_pk_bf16_f32 v148, v165, v166
	v_lshlrev_b32_e32 v165, 16, v109
	v_and_b32_e32 v166, s28, v109
	v_mul_f32_e32 v165, v165, v134
	v_mul_f32_e32 v166, v166, v135
	v_cvt_pk_bf16_f32 v149, v165, v166
	v_lshlrev_b32_e32 v165, 16, v110
	v_and_b32_e32 v166, s28, v110
	v_mul_f32_e32 v165, v165, v136
	v_mul_f32_e32 v166, v166, v137
	v_cvt_pk_bf16_f32 v150, v165, v166
	v_lshlrev_b32_e32 v165, 16, v111
	v_and_b32_e32 v166, s28, v111
	v_mul_f32_e32 v165, v165, v138
	v_mul_f32_e32 v166, v166, v139
	v_cvt_pk_bf16_f32 v151, v165, v166
	s_nop 1
	v_mfma_f32_16x16x32_bf16 v[156:159], v[148:151], v[124:127], v[156:159]
	s_waitcnt lgkmcnt(0)
	v_lshlrev_b32_e32 v165, 16, v112
	v_and_b32_e32 v166, s28, v112
	v_mul_f32_e32 v165, v165, v140
	v_mul_f32_e32 v166, v166, v141
	v_cvt_pk_bf16_f32 v152, v165, v166
	v_lshlrev_b32_e32 v165, 16, v113
	v_and_b32_e32 v166, s28, v113
	v_mul_f32_e32 v165, v165, v142
	v_mul_f32_e32 v166, v166, v143
	v_cvt_pk_bf16_f32 v153, v165, v166
	v_lshlrev_b32_e32 v165, 16, v114
	v_and_b32_e32 v166, s28, v114
	v_mul_f32_e32 v165, v165, v144
	v_mul_f32_e32 v166, v166, v145
	v_cvt_pk_bf16_f32 v154, v165, v166
	v_lshlrev_b32_e32 v165, 16, v115
	v_and_b32_e32 v166, s28, v115
	v_mul_f32_e32 v165, v165, v146
	v_mul_f32_e32 v166, v166, v147
	v_cvt_pk_bf16_f32 v155, v165, v166
	s_nop 1
	v_mfma_f32_16x16x32_bf16 v[156:159], v[152:155], v[128:131], v[156:159]
	global_load_dwordx4 v[100:103], v160, s[44:45]
	global_load_dwordx4 v[104:107], v160, s[44:45] offset:64
	global_load_dwordx4 v[108:111], v160, s[44:45] offset:128
	global_load_dwordx4 v[112:115], v160, s[44:45] offset:192
	global_load_dwordx4 v[116:119], v160, s[46:47]
	global_load_dwordx4 v[120:123], v160, s[46:47] offset:64
	global_load_dwordx4 v[124:127], v160, s[46:47] offset:128
	global_load_dwordx4 v[128:131], v160, s[46:47] offset:192
	s_add_u32 s44, s44, s98
	s_addc_u32 s45, s45, s92
	s_add_u32 s46, s46, s99
	s_addc_u32 s47, s47, s92
	s_waitcnt vmcnt(36)
	s_xor_b32 s100, s39, 4
	s_lshl_b32 s100, s100, 9
	v_add_u32_e32 v170, s100, v163
	s_nop 0
	ds_read_b128 v[132:135], v170
	ds_read_b128 v[136:139], v170 offset:16
	v_bfe_u32 v165, v156, 16, 1
	v_add3_u32 v165, v156, v165, s27
	global_store_short_d16_hi v162, v165, s[48:49] offset:0
	v_bfe_u32 v166, v157, 16, 1
	v_add3_u32 v166, v157, v166, s27
	global_store_short_d16_hi v162, v166, s[48:49] offset:256
	v_bfe_u32 v167, v158, 16, 1
	v_add3_u32 v167, v158, v167, s27
	global_store_short_d16_hi v162, v167, s[48:49] offset:512
	v_bfe_u32 v168, v159, 16, 1
	v_add3_u32 v168, v159, v168, s27
	global_store_short_d16_hi v162, v168, s[48:49] offset:768
	s_add_u32 s48, s48, s6
	s_addc_u32 s49, s49, s92
	v_mul_f32_e32 v164, 0x3fb8aa3b, v175
	v_exp_f32_e32 v164, v164
	s_nop 0
	v_mul_f32_e32 v156, v156, v164
	v_mul_f32_e32 v157, v157, v164
	v_mul_f32_e32 v158, v158, v164
	v_mul_f32_e32 v159, v159, v164
	ds_read_b128 v[140:143], v170 offset:128
	ds_read_b128 v[144:147], v170 offset:144
	s_waitcnt lgkmcnt(2)
	v_lshlrev_b32_e32 v165, 16, v4
	v_and_b32_e32 v166, s28, v4
	v_mul_f32_e32 v165, v165, v132
	v_mul_f32_e32 v166, v166, v133
	v_cvt_pk_bf16_f32 v148, v165, v166
	v_lshlrev_b32_e32 v165, 16, v5
	v_and_b32_e32 v166, s28, v5
	v_mul_f32_e32 v165, v165, v134
	v_mul_f32_e32 v166, v166, v135
	v_cvt_pk_bf16_f32 v149, v165, v166
	v_lshlrev_b32_e32 v165, 16, v6
	v_and_b32_e32 v166, s28, v6
	v_mul_f32_e32 v165, v165, v136
	v_mul_f32_e32 v166, v166, v137
	v_cvt_pk_bf16_f32 v150, v165, v166
	v_lshlrev_b32_e32 v165, 16, v7
	v_and_b32_e32 v166, s28, v7
	v_mul_f32_e32 v165, v165, v138
	v_mul_f32_e32 v166, v166, v139
	v_cvt_pk_bf16_f32 v151, v165, v166
	s_nop 1
	v_mfma_f32_16x16x32_bf16 v[156:159], v[148:151], v[20:23], v[156:159]
	ds_read_b128 v[132:135], v170 offset:256
	ds_read_b128 v[136:139], v170 offset:272
	s_waitcnt lgkmcnt(2)
	v_lshlrev_b32_e32 v165, 16, v8
	v_and_b32_e32 v166, s28, v8
	v_mul_f32_e32 v165, v165, v140
	v_mul_f32_e32 v166, v166, v141
	v_cvt_pk_bf16_f32 v152, v165, v166
	v_lshlrev_b32_e32 v165, 16, v9
	v_and_b32_e32 v166, s28, v9
	v_mul_f32_e32 v165, v165, v142
	v_mul_f32_e32 v166, v166, v143
	v_cvt_pk_bf16_f32 v153, v165, v166
	v_lshlrev_b32_e32 v165, 16, v10
	v_and_b32_e32 v166, s28, v10
	v_mul_f32_e32 v165, v165, v144
	v_mul_f32_e32 v166, v166, v145
	v_cvt_pk_bf16_f32 v154, v165, v166
	v_lshlrev_b32_e32 v165, 16, v11
	v_and_b32_e32 v166, s28, v11
	v_mul_f32_e32 v165, v165, v146
	v_mul_f32_e32 v166, v166, v147
	v_cvt_pk_bf16_f32 v155, v165, v166
	s_nop 1
	v_mfma_f32_16x16x32_bf16 v[156:159], v[152:155], v[24:27], v[156:159]
	ds_read_b128 v[140:143], v170 offset:384
	ds_read_b128 v[144:147], v170 offset:400
	s_waitcnt lgkmcnt(2)
	v_lshlrev_b32_e32 v165, 16, v12
	v_and_b32_e32 v166, s28, v12
	v_mul_f32_e32 v165, v165, v132
	v_mul_f32_e32 v166, v166, v133
	v_cvt_pk_bf16_f32 v148, v165, v166
	v_lshlrev_b32_e32 v165, 16, v13
	v_and_b32_e32 v166, s28, v13
	v_mul_f32_e32 v165, v165, v134
	v_mul_f32_e32 v166, v166, v135
	v_cvt_pk_bf16_f32 v149, v165, v166
	v_lshlrev_b32_e32 v165, 16, v14
	v_and_b32_e32 v166, s28, v14
	v_mul_f32_e32 v165, v165, v136
	v_mul_f32_e32 v166, v166, v137
	v_cvt_pk_bf16_f32 v150, v165, v166
	v_lshlrev_b32_e32 v165, 16, v15
	v_and_b32_e32 v166, s28, v15
	v_mul_f32_e32 v165, v165, v138
	v_mul_f32_e32 v166, v166, v139
	v_cvt_pk_bf16_f32 v151, v165, v166
	s_nop 1
	v_mfma_f32_16x16x32_bf16 v[156:159], v[148:151], v[28:31], v[156:159]
	s_waitcnt lgkmcnt(0)
	v_lshlrev_b32_e32 v165, 16, v16
	v_and_b32_e32 v166, s28, v16
	v_mul_f32_e32 v165, v165, v140
	v_mul_f32_e32 v166, v166, v141
	v_cvt_pk_bf16_f32 v152, v165, v166
	v_lshlrev_b32_e32 v165, 16, v17
	v_and_b32_e32 v166, s28, v17
	v_mul_f32_e32 v165, v165, v142
	v_mul_f32_e32 v166, v166, v143
	v_cvt_pk_bf16_f32 v153, v165, v166
	v_lshlrev_b32_e32 v165, 16, v18
	v_and_b32_e32 v166, s28, v18
	v_mul_f32_e32 v165, v165, v144
	v_mul_f32_e32 v166, v166, v145
	v_cvt_pk_bf16_f32 v154, v165, v166
	v_lshlrev_b32_e32 v165, 16, v19
	v_and_b32_e32 v166, s28, v19
	v_mul_f32_e32 v165, v165, v146
	v_mul_f32_e32 v166, v166, v147
	v_cvt_pk_bf16_f32 v155, v165, v166
	s_nop 1
	v_mfma_f32_16x16x32_bf16 v[156:159], v[152:155], v[32:35], v[156:159]
	s_nop 7
	s_waitcnt vmcnt(28)
	s_xor_b32 s100, s39, 5
	s_lshl_b32 s100, s100, 9
	v_add_u32_e32 v170, s100, v163
	s_nop 0
	ds_read_b128 v[132:135], v170
	ds_read_b128 v[136:139], v170 offset:16
	v_bfe_u32 v165, v156, 16, 1
	v_add3_u32 v165, v156, v165, s27
	global_store_short_d16_hi v162, v165, s[48:49] offset:0
	v_bfe_u32 v166, v157, 16, 1
	v_add3_u32 v166, v157, v166, s27
	global_store_short_d16_hi v162, v166, s[48:49] offset:256
	v_bfe_u32 v167, v158, 16, 1
	v_add3_u32 v167, v158, v167, s27
	global_store_short_d16_hi v162, v167, s[48:49] offset:512
	v_bfe_u32 v168, v159, 16, 1
	v_add3_u32 v168, v159, v168, s27
	global_store_short_d16_hi v162, v168, s[48:49] offset:768
	s_add_u32 s48, s48, s6
	s_addc_u32 s49, s49, s92
	v_mul_f32_e32 v164, 0x3fb8aa3b, v176
	v_exp_f32_e32 v164, v164
	s_nop 0
	v_mul_f32_e32 v156, v156, v164
	v_mul_f32_e32 v157, v157, v164
	v_mul_f32_e32 v158, v158, v164
	v_mul_f32_e32 v159, v159, v164
	ds_read_b128 v[140:143], v170 offset:128
	ds_read_b128 v[144:147], v170 offset:144
	s_waitcnt lgkmcnt(2)
	v_lshlrev_b32_e32 v165, 16, v36
	v_and_b32_e32 v166, s28, v36
	v_mul_f32_e32 v165, v165, v132
	v_mul_f32_e32 v166, v166, v133
	v_cvt_pk_bf16_f32 v148, v165, v166
	v_lshlrev_b32_e32 v165, 16, v37
	v_and_b32_e32 v166, s28, v37
	v_mul_f32_e32 v165, v165, v134
	v_mul_f32_e32 v166, v166, v135
	v_cvt_pk_bf16_f32 v149, v165, v166
	v_lshlrev_b32_e32 v165, 16, v38
	v_and_b32_e32 v166, s28, v38
	v_mul_f32_e32 v165, v165, v136
	v_mul_f32_e32 v166, v166, v137
	v_cvt_pk_bf16_f32 v150, v165, v166
	v_lshlrev_b32_e32 v165, 16, v39
	v_and_b32_e32 v166, s28, v39
	v_mul_f32_e32 v165, v165, v138
	v_mul_f32_e32 v166, v166, v139
	v_cvt_pk_bf16_f32 v151, v165, v166
	s_nop 1
	v_mfma_f32_16x16x32_bf16 v[156:159], v[148:151], v[52:55], v[156:159]
	ds_read_b128 v[132:135], v170 offset:256
	ds_read_b128 v[136:139], v170 offset:272
	s_waitcnt lgkmcnt(2)
	v_lshlrev_b32_e32 v165, 16, v40
	v_and_b32_e32 v166, s28, v40
	v_mul_f32_e32 v165, v165, v140
	v_mul_f32_e32 v166, v166, v141
	v_cvt_pk_bf16_f32 v152, v165, v166
	v_lshlrev_b32_e32 v165, 16, v41
	v_and_b32_e32 v166, s28, v41
	v_mul_f32_e32 v165, v165, v142
	v_mul_f32_e32 v166, v166, v143
	v_cvt_pk_bf16_f32 v153, v165, v166
	v_lshlrev_b32_e32 v165, 16, v42
	v_and_b32_e32 v166, s28, v42
	v_mul_f32_e32 v165, v165, v144
	v_mul_f32_e32 v166, v166, v145
	v_cvt_pk_bf16_f32 v154, v165, v166
	v_lshlrev_b32_e32 v165, 16, v43
	v_and_b32_e32 v166, s28, v43
	v_mul_f32_e32 v165, v165, v146
	v_mul_f32_e32 v166, v166, v147
	v_cvt_pk_bf16_f32 v155, v165, v166
	s_nop 1
	v_mfma_f32_16x16x32_bf16 v[156:159], v[152:155], v[56:59], v[156:159]
	ds_read_b128 v[140:143], v170 offset:384
	ds_read_b128 v[144:147], v170 offset:400
	s_waitcnt lgkmcnt(2)
	v_lshlrev_b32_e32 v165, 16, v44
	v_and_b32_e32 v166, s28, v44
	v_mul_f32_e32 v165, v165, v132
	v_mul_f32_e32 v166, v166, v133
	v_cvt_pk_bf16_f32 v148, v165, v166
	v_lshlrev_b32_e32 v165, 16, v45
	v_and_b32_e32 v166, s28, v45
	v_mul_f32_e32 v165, v165, v134
	v_mul_f32_e32 v166, v166, v135
	v_cvt_pk_bf16_f32 v149, v165, v166
	v_lshlrev_b32_e32 v165, 16, v46
	v_and_b32_e32 v166, s28, v46
	v_mul_f32_e32 v165, v165, v136
	v_mul_f32_e32 v166, v166, v137
	v_cvt_pk_bf16_f32 v150, v165, v166
	v_lshlrev_b32_e32 v165, 16, v47
	v_and_b32_e32 v166, s28, v47
	v_mul_f32_e32 v165, v165, v138
	v_mul_f32_e32 v166, v166, v139
	v_cvt_pk_bf16_f32 v151, v165, v166
	s_nop 1
	v_mfma_f32_16x16x32_bf16 v[156:159], v[148:151], v[60:63], v[156:159]
	s_waitcnt lgkmcnt(0)
	v_lshlrev_b32_e32 v165, 16, v48
	v_and_b32_e32 v166, s28, v48
	v_mul_f32_e32 v165, v165, v140
	v_mul_f32_e32 v166, v166, v141
	v_cvt_pk_bf16_f32 v152, v165, v166
	v_lshlrev_b32_e32 v165, 16, v49
	v_and_b32_e32 v166, s28, v49
	v_mul_f32_e32 v165, v165, v142
	v_mul_f32_e32 v166, v166, v143
	v_cvt_pk_bf16_f32 v153, v165, v166
	v_lshlrev_b32_e32 v165, 16, v50
	v_and_b32_e32 v166, s28, v50
	v_mul_f32_e32 v165, v165, v144
	v_mul_f32_e32 v166, v166, v145
	v_cvt_pk_bf16_f32 v154, v165, v166
	v_lshlrev_b32_e32 v165, 16, v51
	v_and_b32_e32 v166, s28, v51
	v_mul_f32_e32 v165, v165, v146
	v_mul_f32_e32 v166, v166, v147
	v_cvt_pk_bf16_f32 v155, v165, v166
	s_nop 1
	v_mfma_f32_16x16x32_bf16 v[156:159], v[152:155], v[64:67], v[156:159]
	s_nop 7
	s_waitcnt vmcnt(20)
	s_xor_b32 s100, s39, 6
	s_lshl_b32 s100, s100, 9
	v_add_u32_e32 v170, s100, v163
	s_nop 0
	ds_read_b128 v[132:135], v170
	ds_read_b128 v[136:139], v170 offset:16
	v_bfe_u32 v165, v156, 16, 1
	v_add3_u32 v165, v156, v165, s27
	global_store_short_d16_hi v162, v165, s[48:49] offset:0
	v_bfe_u32 v166, v157, 16, 1
	v_add3_u32 v166, v157, v166, s27
	global_store_short_d16_hi v162, v166, s[48:49] offset:256
	v_bfe_u32 v167, v158, 16, 1
	v_add3_u32 v167, v158, v167, s27
	global_store_short_d16_hi v162, v167, s[48:49] offset:512
	v_bfe_u32 v168, v159, 16, 1
	v_add3_u32 v168, v159, v168, s27
	global_store_short_d16_hi v162, v168, s[48:49] offset:768
	s_add_u32 s48, s48, s6
	s_addc_u32 s49, s49, s92
	v_mul_f32_e32 v164, 0x3fb8aa3b, v177
	v_exp_f32_e32 v164, v164
	s_nop 0
	v_mul_f32_e32 v156, v156, v164
	v_mul_f32_e32 v157, v157, v164
	v_mul_f32_e32 v158, v158, v164
	v_mul_f32_e32 v159, v159, v164
	ds_read_b128 v[140:143], v170 offset:128
	ds_read_b128 v[144:147], v170 offset:144
	s_waitcnt lgkmcnt(2)
	v_lshlrev_b32_e32 v165, 16, v68
	v_and_b32_e32 v166, s28, v68
	v_mul_f32_e32 v165, v165, v132
	v_mul_f32_e32 v166, v166, v133
	v_cvt_pk_bf16_f32 v148, v165, v166
	v_lshlrev_b32_e32 v165, 16, v69
	v_and_b32_e32 v166, s28, v69
	v_mul_f32_e32 v165, v165, v134
	v_mul_f32_e32 v166, v166, v135
	v_cvt_pk_bf16_f32 v149, v165, v166
	v_lshlrev_b32_e32 v165, 16, v70
	v_and_b32_e32 v166, s28, v70
	v_mul_f32_e32 v165, v165, v136
	v_mul_f32_e32 v166, v166, v137
	v_cvt_pk_bf16_f32 v150, v165, v166
	v_lshlrev_b32_e32 v165, 16, v71
	v_and_b32_e32 v166, s28, v71
	v_mul_f32_e32 v165, v165, v138
	v_mul_f32_e32 v166, v166, v139
	v_cvt_pk_bf16_f32 v151, v165, v166
	s_nop 1
	v_mfma_f32_16x16x32_bf16 v[156:159], v[148:151], v[84:87], v[156:159]
	ds_read_b128 v[132:135], v170 offset:256
	ds_read_b128 v[136:139], v170 offset:272
	s_waitcnt lgkmcnt(2)
	v_lshlrev_b32_e32 v165, 16, v72
	v_and_b32_e32 v166, s28, v72
	v_mul_f32_e32 v165, v165, v140
	v_mul_f32_e32 v166, v166, v141
	v_cvt_pk_bf16_f32 v152, v165, v166
	v_lshlrev_b32_e32 v165, 16, v73
	v_and_b32_e32 v166, s28, v73
	v_mul_f32_e32 v165, v165, v142
	v_mul_f32_e32 v166, v166, v143
	v_cvt_pk_bf16_f32 v153, v165, v166
	v_lshlrev_b32_e32 v165, 16, v74
	v_and_b32_e32 v166, s28, v74
	v_mul_f32_e32 v165, v165, v144
	v_mul_f32_e32 v166, v166, v145
	v_cvt_pk_bf16_f32 v154, v165, v166
	v_lshlrev_b32_e32 v165, 16, v75
	v_and_b32_e32 v166, s28, v75
	v_mul_f32_e32 v165, v165, v146
	v_mul_f32_e32 v166, v166, v147
	v_cvt_pk_bf16_f32 v155, v165, v166
	s_nop 1
	v_mfma_f32_16x16x32_bf16 v[156:159], v[152:155], v[88:91], v[156:159]
	ds_read_b128 v[140:143], v170 offset:384
	ds_read_b128 v[144:147], v170 offset:400
	s_waitcnt lgkmcnt(2)
	v_lshlrev_b32_e32 v165, 16, v76
	v_and_b32_e32 v166, s28, v76
	v_mul_f32_e32 v165, v165, v132
	v_mul_f32_e32 v166, v166, v133
	v_cvt_pk_bf16_f32 v148, v165, v166
	v_lshlrev_b32_e32 v165, 16, v77
	v_and_b32_e32 v166, s28, v77
	v_mul_f32_e32 v165, v165, v134
	v_mul_f32_e32 v166, v166, v135
	v_cvt_pk_bf16_f32 v149, v165, v166
	v_lshlrev_b32_e32 v165, 16, v78
	v_and_b32_e32 v166, s28, v78
	v_mul_f32_e32 v165, v165, v136
	v_mul_f32_e32 v166, v166, v137
	v_cvt_pk_bf16_f32 v150, v165, v166
	v_lshlrev_b32_e32 v165, 16, v79
	v_and_b32_e32 v166, s28, v79
	v_mul_f32_e32 v165, v165, v138
	v_mul_f32_e32 v166, v166, v139
	v_cvt_pk_bf16_f32 v151, v165, v166
	s_nop 1
	v_mfma_f32_16x16x32_bf16 v[156:159], v[148:151], v[92:95], v[156:159]
	s_waitcnt lgkmcnt(0)
	v_lshlrev_b32_e32 v165, 16, v80
	v_and_b32_e32 v166, s28, v80
	v_mul_f32_e32 v165, v165, v140
	v_mul_f32_e32 v166, v166, v141
	v_cvt_pk_bf16_f32 v152, v165, v166
	v_lshlrev_b32_e32 v165, 16, v81
	v_and_b32_e32 v166, s28, v81
	v_mul_f32_e32 v165, v165, v142
	v_mul_f32_e32 v166, v166, v143
	v_cvt_pk_bf16_f32 v153, v165, v166
	v_lshlrev_b32_e32 v165, 16, v82
	v_and_b32_e32 v166, s28, v82
	v_mul_f32_e32 v165, v165, v144
	v_mul_f32_e32 v166, v166, v145
	v_cvt_pk_bf16_f32 v154, v165, v166
	v_lshlrev_b32_e32 v165, 16, v83
	v_and_b32_e32 v166, s28, v83
	v_mul_f32_e32 v165, v165, v146
	v_mul_f32_e32 v166, v166, v147
	v_cvt_pk_bf16_f32 v155, v165, v166
	s_nop 1
	v_mfma_f32_16x16x32_bf16 v[156:159], v[152:155], v[96:99], v[156:159]
	s_nop 7
	s_waitcnt vmcnt(12)
	s_xor_b32 s100, s39, 7
	s_lshl_b32 s100, s100, 9
	v_add_u32_e32 v170, s100, v163
	s_nop 0
	ds_read_b128 v[132:135], v170
	ds_read_b128 v[136:139], v170 offset:16
	v_bfe_u32 v165, v156, 16, 1
	v_add3_u32 v165, v156, v165, s27
	global_store_short_d16_hi v162, v165, s[48:49] offset:0
	v_bfe_u32 v166, v157, 16, 1
	v_add3_u32 v166, v157, v166, s27
	global_store_short_d16_hi v162, v166, s[48:49] offset:256
	v_bfe_u32 v167, v158, 16, 1
	v_add3_u32 v167, v158, v167, s27
	global_store_short_d16_hi v162, v167, s[48:49] offset:512
	v_bfe_u32 v168, v159, 16, 1
	v_add3_u32 v168, v159, v168, s27
	global_store_short_d16_hi v162, v168, s[48:49] offset:768
	s_add_u32 s48, s48, s6
	s_addc_u32 s49, s49, s92
	v_mul_f32_e32 v164, 0x3fb8aa3b, v178
	v_exp_f32_e32 v164, v164
	s_nop 0
	v_mul_f32_e32 v156, v156, v164
	v_mul_f32_e32 v157, v157, v164
	v_mul_f32_e32 v158, v158, v164
	v_mul_f32_e32 v159, v159, v164
	ds_read_b128 v[140:143], v170 offset:128
	ds_read_b128 v[144:147], v170 offset:144
	s_waitcnt lgkmcnt(2)
	v_lshlrev_b32_e32 v165, 16, v100
	v_and_b32_e32 v166, s28, v100
	v_mul_f32_e32 v165, v165, v132
	v_mul_f32_e32 v166, v166, v133
	v_cvt_pk_bf16_f32 v148, v165, v166
	v_lshlrev_b32_e32 v165, 16, v101
	v_and_b32_e32 v166, s28, v101
	v_mul_f32_e32 v165, v165, v134
	v_mul_f32_e32 v166, v166, v135
	v_cvt_pk_bf16_f32 v149, v165, v166
	v_lshlrev_b32_e32 v165, 16, v102
	v_and_b32_e32 v166, s28, v102
	v_mul_f32_e32 v165, v165, v136
	v_mul_f32_e32 v166, v166, v137
	v_cvt_pk_bf16_f32 v150, v165, v166
	v_lshlrev_b32_e32 v165, 16, v103
	v_and_b32_e32 v166, s28, v103
	v_mul_f32_e32 v165, v165, v138
	v_mul_f32_e32 v166, v166, v139
	v_cvt_pk_bf16_f32 v151, v165, v166
	s_nop 1
	v_mfma_f32_16x16x32_bf16 v[156:159], v[148:151], v[116:119], v[156:159]
	ds_read_b128 v[132:135], v170 offset:256
	ds_read_b128 v[136:139], v170 offset:272
	s_waitcnt lgkmcnt(2)
	v_lshlrev_b32_e32 v165, 16, v104
	v_and_b32_e32 v166, s28, v104
	v_mul_f32_e32 v165, v165, v140
	v_mul_f32_e32 v166, v166, v141
	v_cvt_pk_bf16_f32 v152, v165, v166
	v_lshlrev_b32_e32 v165, 16, v105
	v_and_b32_e32 v166, s28, v105
	v_mul_f32_e32 v165, v165, v142
	v_mul_f32_e32 v166, v166, v143
	v_cvt_pk_bf16_f32 v153, v165, v166
	v_lshlrev_b32_e32 v165, 16, v106
	v_and_b32_e32 v166, s28, v106
	v_mul_f32_e32 v165, v165, v144
	v_mul_f32_e32 v166, v166, v145
	v_cvt_pk_bf16_f32 v154, v165, v166
	v_lshlrev_b32_e32 v165, 16, v107
	v_and_b32_e32 v166, s28, v107
	v_mul_f32_e32 v165, v165, v146
	v_mul_f32_e32 v166, v166, v147
	v_cvt_pk_bf16_f32 v155, v165, v166
	s_nop 1
	v_mfma_f32_16x16x32_bf16 v[156:159], v[152:155], v[120:123], v[156:159]
	ds_read_b128 v[140:143], v170 offset:384
	ds_read_b128 v[144:147], v170 offset:400
	s_waitcnt lgkmcnt(2)
	v_lshlrev_b32_e32 v165, 16, v108
	v_and_b32_e32 v166, s28, v108
	v_mul_f32_e32 v165, v165, v132
	v_mul_f32_e32 v166, v166, v133
	v_cvt_pk_bf16_f32 v148, v165, v166
	v_lshlrev_b32_e32 v165, 16, v109
	v_and_b32_e32 v166, s28, v109
	v_mul_f32_e32 v165, v165, v134
	v_mul_f32_e32 v166, v166, v135
	v_cvt_pk_bf16_f32 v149, v165, v166
	v_lshlrev_b32_e32 v165, 16, v110
	v_and_b32_e32 v166, s28, v110
	v_mul_f32_e32 v165, v165, v136
	v_mul_f32_e32 v166, v166, v137
	v_cvt_pk_bf16_f32 v150, v165, v166
	v_lshlrev_b32_e32 v165, 16, v111
	v_and_b32_e32 v166, s28, v111
	v_mul_f32_e32 v165, v165, v138
	v_mul_f32_e32 v166, v166, v139
	v_cvt_pk_bf16_f32 v151, v165, v166
	s_nop 1
	v_mfma_f32_16x16x32_bf16 v[156:159], v[148:151], v[124:127], v[156:159]
	s_waitcnt lgkmcnt(0)
	v_lshlrev_b32_e32 v165, 16, v112
	v_and_b32_e32 v166, s28, v112
	v_mul_f32_e32 v165, v165, v140
	v_mul_f32_e32 v166, v166, v141
	v_cvt_pk_bf16_f32 v152, v165, v166
	v_lshlrev_b32_e32 v165, 16, v113
	v_and_b32_e32 v166, s28, v113
	v_mul_f32_e32 v165, v165, v142
	v_mul_f32_e32 v166, v166, v143
	v_cvt_pk_bf16_f32 v153, v165, v166
	v_lshlrev_b32_e32 v165, 16, v114
	v_and_b32_e32 v166, s28, v114
	v_mul_f32_e32 v165, v165, v144
	v_mul_f32_e32 v166, v166, v145
	v_cvt_pk_bf16_f32 v154, v165, v166
	v_lshlrev_b32_e32 v165, 16, v115
	v_and_b32_e32 v166, s28, v115
	v_mul_f32_e32 v165, v165, v146
	v_mul_f32_e32 v166, v166, v147
	v_cvt_pk_bf16_f32 v155, v165, v166
	s_nop 1
	v_mfma_f32_16x16x32_bf16 v[156:159], v[152:155], v[128:131], v[156:159]
	s_nop 7
	s_branch .LBB0_632
.Lch_ctx:
	v_and_b32_e32 v228, 63, v206
	v_lshrrev_b32_e32 v229, 6, v206
	v_and_b32_e32 v0, 15, v228
	v_readfirstlane_b32 s40, v229
	v_lshrrev_b32_e32 v1, 4, v228
	s_sub_u32 s38, s35, 0x80
	s_and_b32 s42, s40, 3
	s_lshr_b32 s43, s40, 2
	s_lshl_b32 s43, s43, 2
	s_lshr_b32 s100, s38, 4
	s_lshl_b32 s101, s100, 1
	s_bfe_u32 s41, s38, 0x30001
	s_and_b32 s39, s38, 1
	s_lshl_b32 s8, s100, 1
	s_add_u32 s8, s8, s36
	s_lshl_b32 s8, s8, 1
	s_add_u32 s8, s8, s39
	s_lshl_b32 s8, s8, 3
	s_add_u32 s8, s8, s41
	s_add_u32 s100, s101, 1
	s_cmp_eq_u32 s39, 0
	s_cselect_b32 s101, s101, s100
	s_cselect_b32 s92, 0, -1
	s_mov_b32 s98, 0xfffe0000
	s_cselect_b32 s98, 0x20000, s98
	s_mov_b32 s99, 0xffff0000
	s_cselect_b32 s99, 0x10000, s99
	s_mov_b32 s6, 0xfffc0000
	s_cselect_b32 s6, 0x40000, s6
	s_mov_b32 s7, 0xffffe000
	s_cselect_b32 s7, 0x2000, s7
	s_lshl_b32 s100, s101, 3
	s_add_u32 s100, s100, s41
	s_lshl_b32 s100, s100, 14
	s_lshl_b32 s9, s42, 12
	s_add_u32 s100, s100, s9
	s_add_u32 s100, s100, 0xc184000
	s_add_u32 s44, s96, s100
	s_addc_u32 s45, s97, 0
	s_lshl_b32 s100, s101, 1
	s_lshr_b32 s9, s41, 2
	s_add_u32 s100, s100, s9
	s_lshl_b32 s100, s100, 15
	s_lshl_b32 s9, s43, 12
	s_add_u32 s100, s100, s9
	s_add_u32 s100, s100, 0xbe84000
	s_add_u32 s46, s96, s100
	s_addc_u32 s47, s97, 0
	s_lshl_b32 s100, s101, 1
	s_add_u32 s100, s100, s39
	s_lshl_b32 s100, s100, 3
	s_add_u32 s100, s100, s41
	s_lshl_b32 s9, s100, 14
	s_lshl_b32 s59, s42, 12
	s_add_u32 s9, s9, s59
	s_lshl_b32 s59, s43, 5
	s_add_u32 s9, s9, s59
	s_add_u32 s9, s9, 0xac84000
	s_add_u32 s48, s96, s9
	s_addc_u32 s49, s97, 0
	s_lshl_b32 s100, s100, 9
	s_add_u32 s9, s100, 0xcae4000
	s_add_u32 s58, s96, s9
	s_addc_u32 s59, s97, 0
	s_cmp_eq_u32 s39, 0
	s_cselect_b32 s9, 0x1fc, 0
	s_add_u32 s58, s58, s9
	s_addc_u32 s59, s59, 0
	global_load_dword v227, v2, s[58:59]
	s_add_u32 s58, s58, s7
	s_addc_u32 s59, s59, s92
	global_load_dword v232, v2, s[58:59]
	s_add_u32 s9, s100, 0xcb44000
	s_add_u32 s58, s96, s9
	s_addc_u32 s59, s97, 0
	s_cmp_eq_u32 s39, 0
	s_cbranch_scc1 .Lch_ctx_fw
	s_sub_u32 s58, s58, 0x2000
	s_subb_u32 s59, s59, 0
.Lch_ctx_fw:
	v_lshrrev_b32_e32 v230, 5, v228
	v_and_b32_e32 v231, 31, v228
	v_lshlrev_b32_e32 v230, 13, v230
	v_lshl_add_u32 v230, v231, 4, v230
	s_lshl_b32 s9, s40, 12
	s_lshl_b32 s100, s7, 1
	s_add_u32 m0, s9, 0x0
	s_nop 0
	global_load_lds_dwordx4 v230, s[58:59]
	v_lshlrev_b32_e32 v3, 8, v0
	v_lshl_add_u32 v3, v1, 4, v3
	v_add_u32_e32 v197, 0x1000, v3
	v_add_u32_e32 v199, 0x2000, v3
	v_add_u32_e32 v204, 0x3000, v3
	v_lshlrev_b32_e32 v205, 11, v1
	v_lshl_add_u32 v205, v0, 2, v205
	v_lshrrev_b32_e32 v221, 1, v205
	v_lshl_add_u32 v226, v1, 5, s9
	v_mov_b32_e32 v188, 0
	v_mov_b32_e32 v189, 0
	v_mov_b32_e32 v190, 0
	v_mov_b32_e32 v191, 0
	v_mov_b32_e32 v192, 0
	v_mov_b32_e32 v193, 0
	v_mov_b32_e32 v194, 0
	v_mov_b32_e32 v195, 0
	v_mov_b32_e32 v200, 0
	v_mov_b32_e32 v201, 0
	v_mov_b32_e32 v202, 0
	v_mov_b32_e32 v203, 0
	v_mov_b32_e32 v222, 0
	v_mov_b32_e32 v223, 0
	v_mov_b32_e32 v224, 0
	v_mov_b32_e32 v225, 0
	global_load_dwordx4 v[4:7], v3, s[44:45]
	global_load_dwordx4 v[8:11], v3, s[44:45] offset:64
	global_load_dwordx4 v[12:15], v3, s[44:45] offset:128
	global_load_dwordx4 v[16:19], v3, s[44:45] offset:192
	global_load_dwordx4 v[20:23], v3, s[46:47]
	global_load_dwordx4 v[24:27], v197, s[46:47]
	global_load_dwordx4 v[28:31], v199, s[46:47]
	global_load_dwordx4 v[32:35], v204, s[46:47]
	global_load_dwordx4 v[36:39], v3, s[46:47] offset:64
	global_load_dwordx4 v[40:43], v197, s[46:47] offset:64
	global_load_dwordx4 v[44:47], v199, s[46:47] offset:64
	global_load_dwordx4 v[48:51], v204, s[46:47] offset:64
	global_load_dwordx4 v[52:55], v3, s[46:47] offset:128
	global_load_dwordx4 v[56:59], v197, s[46:47] offset:128
	global_load_dwordx4 v[60:63], v199, s[46:47] offset:128
	global_load_dwordx4 v[64:67], v204, s[46:47] offset:128
	global_load_dwordx4 v[68:71], v3, s[46:47] offset:192
	global_load_dwordx4 v[72:75], v197, s[46:47] offset:192
	global_load_dwordx4 v[76:79], v199, s[46:47] offset:192
	global_load_dwordx4 v[80:83], v204, s[46:47] offset:192
	s_add_u32 s44, s44, s98
	s_addc_u32 s45, s45, s92
	s_add_u32 s46, s46, s99
	s_addc_u32 s47, s47, s92
	global_load_dwordx4 v[84:87], v3, s[44:45]
	global_load_dwordx4 v[88:91], v3, s[44:45] offset:64
	global_load_dwordx4 v[92:95], v3, s[44:45] offset:128
	global_load_dwordx4 v[96:99], v3, s[44:45] offset:192
	global_load_dwordx4 v[100:103], v3, s[46:47]
	global_load_dwordx4 v[104:107], v197, s[46:47]
	global_load_dwordx4 v[108:111], v199, s[46:47]
	global_load_dwordx4 v[112:115], v204, s[46:47]
	global_load_dwordx4 v[116:119], v3, s[46:47] offset:64
	global_load_dwordx4 v[120:123], v197, s[46:47] offset:64
	global_load_dwordx4 v[124:127], v199, s[46:47] offset:64
	global_load_dwordx4 v[128:131], v204, s[46:47] offset:64
	global_load_dwordx4 v[132:135], v3, s[46:47] offset:128
	global_load_dwordx4 v[136:139], v197, s[46:47] offset:128
	global_load_dwordx4 v[140:143], v199, s[46:47] offset:128
	global_load_dwordx4 v[144:147], v204, s[46:47] offset:128
	global_load_dwordx4 v[148:151], v3, s[46:47] offset:192
	global_load_dwordx4 v[152:155], v197, s[46:47] offset:192
	global_load_dwordx4 v[156:159], v199, s[46:47] offset:192
	global_load_dwordx4 v[160:163], v204, s[46:47] offset:192
	s_add_u32 s44, s44, s98
	s_addc_u32 s45, s45, s92
	s_add_u32 s46, s46, s99
	s_addc_u32 s47, s47, s92
	s_waitcnt vmcnt(20)
	s_xor_b32 s100, s39, 0
	s_lshl_b32 s100, s100, 9
	v_add_u32_e32 v233, s100, v226
	s_nop 0
	ds_read_b128 v[164:167], v233
	ds_read_b128 v[168:171], v233 offset:16
	v_bfe_u32 v228, v188, 16, 1
	v_add3_u32 v228, v188, v228, s27
	global_store_short_d16_hi v221, v228, s[48:49] offset:0
	v_bfe_u32 v229, v189, 16, 1
	v_add3_u32 v229, v189, v229, s27
	global_store_short_d16_hi v221, v229, s[48:49] offset:256
	v_bfe_u32 v230, v190, 16, 1
	v_add3_u32 v230, v190, v230, s27
	global_store_short_d16_hi v221, v230, s[48:49] offset:512
	v_bfe_u32 v231, v191, 16, 1
	v_add3_u32 v231, v191, v231, s27
	global_store_short_d16_hi v221, v231, s[48:49] offset:768
	v_bfe_u32 v228, v192, 16, 1
	v_add3_u32 v228, v192, v228, s27
	global_store_short_d16_hi v221, v228, s[48:49] offset:32
	v_bfe_u32 v229, v193, 16, 1
	v_add3_u32 v229, v193, v229, s27
	global_store_short_d16_hi v221, v229, s[48:49] offset:288
	v_bfe_u32 v230, v194, 16, 1
	v_add3_u32 v230, v194, v230, s27
	global_store_short_d16_hi v221, v230, s[48:49] offset:544
	v_bfe_u32 v231, v195, 16, 1
	v_add3_u32 v231, v195, v231, s27
	global_store_short_d16_hi v221, v231, s[48:49] offset:800
	v_bfe_u32 v228, v200, 16, 1
	v_add3_u32 v228, v200, v228, s27
	global_store_short_d16_hi v221, v228, s[48:49] offset:64
	v_bfe_u32 v229, v201, 16, 1
	v_add3_u32 v229, v201, v229, s27
	global_store_short_d16_hi v221, v229, s[48:49] offset:320
	v_bfe_u32 v230, v202, 16, 1
	v_add3_u32 v230, v202, v230, s27
	global_store_short_d16_hi v221, v230, s[48:49] offset:576
	v_bfe_u32 v231, v203, 16, 1
	v_add3_u32 v231, v203, v231, s27
	global_store_short_d16_hi v221, v231, s[48:49] offset:832
	v_bfe_u32 v228, v222, 16, 1
	v_add3_u32 v228, v222, v228, s27
	global_store_short_d16_hi v221, v228, s[48:49] offset:96
	v_bfe_u32 v229, v223, 16, 1
	v_add3_u32 v229, v223, v229, s27
	global_store_short_d16_hi v221, v229, s[48:49] offset:352
	v_bfe_u32 v230, v224, 16, 1
	v_add3_u32 v230, v224, v230, s27
	global_store_short_d16_hi v221, v230, s[48:49] offset:608
	v_bfe_u32 v231, v225, 16, 1
	v_add3_u32 v231, v225, v231, s27
	global_store_short_d16_hi v221, v231, s[48:49] offset:864
	s_add_u32 s48, s48, s6
	s_addc_u32 s49, s49, s92
	v_mul_f32_e32 v227, 0x3fb8aa3b, v227
	v_exp_f32_e32 v227, v227
	s_nop 0
	v_mul_f32_e32 v188, v188, v227
	v_mul_f32_e32 v189, v189, v227
	v_mul_f32_e32 v190, v190, v227
	v_mul_f32_e32 v191, v191, v227
	v_mul_f32_e32 v192, v192, v227
	v_mul_f32_e32 v193, v193, v227
	v_mul_f32_e32 v194, v194, v227
	v_mul_f32_e32 v195, v195, v227
	v_mul_f32_e32 v200, v200, v227
	v_mul_f32_e32 v201, v201, v227
	v_mul_f32_e32 v202, v202, v227
	v_mul_f32_e32 v203, v203, v227
	v_mul_f32_e32 v222, v222, v227
	v_mul_f32_e32 v223, v223, v227
	v_mul_f32_e32 v224, v224, v227
	v_mul_f32_e32 v225, v225, v227
	ds_read_b128 v[172:175], v233 offset:128
	ds_read_b128 v[176:179], v233 offset:144
	s_waitcnt lgkmcnt(2)
	v_lshlrev_b32_e32 v228, 16, v4
	v_and_b32_e32 v229, s28, v4
	v_mul_f32_e32 v228, v228, v164
	v_mul_f32_e32 v229, v229, v165
	v_cvt_pk_bf16_f32 v180, v228, v229
	v_lshlrev_b32_e32 v228, 16, v5
	v_and_b32_e32 v229, s28, v5
	v_mul_f32_e32 v228, v228, v166
	v_mul_f32_e32 v229, v229, v167
	v_cvt_pk_bf16_f32 v181, v228, v229
	v_lshlrev_b32_e32 v228, 16, v6
	v_and_b32_e32 v229, s28, v6
	v_mul_f32_e32 v228, v228, v168
	v_mul_f32_e32 v229, v229, v169
	v_cvt_pk_bf16_f32 v182, v228, v229
	v_lshlrev_b32_e32 v228, 16, v7
	v_and_b32_e32 v229, s28, v7
	v_mul_f32_e32 v228, v228, v170
	v_mul_f32_e32 v229, v229, v171
	v_cvt_pk_bf16_f32 v183, v228, v229
	s_nop 1
	v_mfma_f32_16x16x32_bf16 v[188:191], v[180:183], v[20:23], v[188:191]
	v_mfma_f32_16x16x32_bf16 v[192:195], v[180:183], v[24:27], v[192:195]
	v_mfma_f32_16x16x32_bf16 v[200:203], v[180:183], v[28:31], v[200:203]
	v_mfma_f32_16x16x32_bf16 v[222:225], v[180:183], v[32:35], v[222:225]
	ds_read_b128 v[164:167], v233 offset:256
	ds_read_b128 v[168:171], v233 offset:272
	s_waitcnt lgkmcnt(2)
	v_lshlrev_b32_e32 v228, 16, v8
	v_and_b32_e32 v229, s28, v8
	v_mul_f32_e32 v228, v228, v172
	v_mul_f32_e32 v229, v229, v173
	v_cvt_pk_bf16_f32 v184, v228, v229
	v_lshlrev_b32_e32 v228, 16, v9
	v_and_b32_e32 v229, s28, v9
	v_mul_f32_e32 v228, v228, v174
	v_mul_f32_e32 v229, v229, v175
	v_cvt_pk_bf16_f32 v185, v228, v229
	v_lshlrev_b32_e32 v228, 16, v10
	v_and_b32_e32 v229, s28, v10
	v_mul_f32_e32 v228, v228, v176
	v_mul_f32_e32 v229, v229, v177
	v_cvt_pk_bf16_f32 v186, v228, v229
	v_lshlrev_b32_e32 v228, 16, v11
	v_and_b32_e32 v229, s28, v11
	v_mul_f32_e32 v228, v228, v178
	v_mul_f32_e32 v229, v229, v179
	v_cvt_pk_bf16_f32 v187, v228, v229
	s_nop 1
	v_mfma_f32_16x16x32_bf16 v[188:191], v[184:187], v[36:39], v[188:191]
	v_mfma_f32_16x16x32_bf16 v[192:195], v[184:187], v[40:43], v[192:195]
	v_mfma_f32_16x16x32_bf16 v[200:203], v[184:187], v[44:47], v[200:203]
	v_mfma_f32_16x16x32_bf16 v[222:225], v[184:187], v[48:51], v[222:225]
	ds_read_b128 v[172:175], v233 offset:384
	ds_read_b128 v[176:179], v233 offset:400
	s_waitcnt lgkmcnt(2)
	v_lshlrev_b32_e32 v228, 16, v12
	v_and_b32_e32 v229, s28, v12
	v_mul_f32_e32 v228, v228, v164
	v_mul_f32_e32 v229, v229, v165
	v_cvt_pk_bf16_f32 v180, v228, v229
	v_lshlrev_b32_e32 v228, 16, v13
	v_and_b32_e32 v229, s28, v13
	v_mul_f32_e32 v228, v228, v166
	v_mul_f32_e32 v229, v229, v167
	v_cvt_pk_bf16_f32 v181, v228, v229
	v_lshlrev_b32_e32 v228, 16, v14
	v_and_b32_e32 v229, s28, v14
	v_mul_f32_e32 v228, v228, v168
	v_mul_f32_e32 v229, v229, v169
	v_cvt_pk_bf16_f32 v182, v228, v229
	v_lshlrev_b32_e32 v228, 16, v15
	v_and_b32_e32 v229, s28, v15
	v_mul_f32_e32 v228, v228, v170
	v_mul_f32_e32 v229, v229, v171
	v_cvt_pk_bf16_f32 v183, v228, v229
	s_nop 1
	v_mfma_f32_16x16x32_bf16 v[188:191], v[180:183], v[52:55], v[188:191]
	v_mfma_f32_16x16x32_bf16 v[192:195], v[180:183], v[56:59], v[192:195]
	v_mfma_f32_16x16x32_bf16 v[200:203], v[180:183], v[60:63], v[200:203]
	v_mfma_f32_16x16x32_bf16 v[222:225], v[180:183], v[64:67], v[222:225]
	s_waitcnt lgkmcnt(0)
	v_lshlrev_b32_e32 v228, 16, v16
	v_and_b32_e32 v229, s28, v16
	v_mul_f32_e32 v228, v228, v172
	v_mul_f32_e32 v229, v229, v173
	v_cvt_pk_bf16_f32 v184, v228, v229
	v_lshlrev_b32_e32 v228, 16, v17
	v_and_b32_e32 v229, s28, v17
	v_mul_f32_e32 v228, v228, v174
	v_mul_f32_e32 v229, v229, v175
	v_cvt_pk_bf16_f32 v185, v228, v229
	v_lshlrev_b32_e32 v228, 16, v18
	v_and_b32_e32 v229, s28, v18
	v_mul_f32_e32 v228, v228, v176
	v_mul_f32_e32 v229, v229, v177
	v_cvt_pk_bf16_f32 v186, v228, v229
	v_lshlrev_b32_e32 v228, 16, v19
	v_and_b32_e32 v229, s28, v19
	v_mul_f32_e32 v228, v228, v178
	v_mul_f32_e32 v229, v229, v179
	v_cvt_pk_bf16_f32 v187, v228, v229
	s_nop 1
	v_mfma_f32_16x16x32_bf16 v[188:191], v[184:187], v[68:71], v[188:191]
	v_mfma_f32_16x16x32_bf16 v[192:195], v[184:187], v[72:75], v[192:195]
	v_mfma_f32_16x16x32_bf16 v[200:203], v[184:187], v[76:79], v[200:203]
	v_mfma_f32_16x16x32_bf16 v[222:225], v[184:187], v[80:83], v[222:225]
	s_nop 7
	s_waitcnt vmcnt(16)
	s_xor_b32 s100, s39, 1
	s_lshl_b32 s100, s100, 9
	v_add_u32_e32 v233, s100, v226
	s_nop 0
	ds_read_b128 v[164:167], v233
	ds_read_b128 v[168:171], v233 offset:16
	v_bfe_u32 v228, v188, 16, 1
	v_add3_u32 v228, v188, v228, s27
	global_store_short_d16_hi v221, v228, s[48:49] offset:0
	v_bfe_u32 v229, v189, 16, 1
	v_add3_u32 v229, v189, v229, s27
	global_store_short_d16_hi v221, v229, s[48:49] offset:256
	v_bfe_u32 v230, v190, 16, 1
	v_add3_u32 v230, v190, v230, s27
	global_store_short_d16_hi v221, v230, s[48:49] offset:512
	v_bfe_u32 v231, v191, 16, 1
	v_add3_u32 v231, v191, v231, s27
	global_store_short_d16_hi v221, v231, s[48:49] offset:768
	v_bfe_u32 v228, v192, 16, 1
	v_add3_u32 v228, v192, v228, s27
	global_store_short_d16_hi v221, v228, s[48:49] offset:32
	v_bfe_u32 v229, v193, 16, 1
	v_add3_u32 v229, v193, v229, s27
	global_store_short_d16_hi v221, v229, s[48:49] offset:288
	v_bfe_u32 v230, v194, 16, 1
	v_add3_u32 v230, v194, v230, s27
	global_store_short_d16_hi v221, v230, s[48:49] offset:544
	v_bfe_u32 v231, v195, 16, 1
	v_add3_u32 v231, v195, v231, s27
	global_store_short_d16_hi v221, v231, s[48:49] offset:800
	v_bfe_u32 v228, v200, 16, 1
	v_add3_u32 v228, v200, v228, s27
	global_store_short_d16_hi v221, v228, s[48:49] offset:64
	v_bfe_u32 v229, v201, 16, 1
	v_add3_u32 v229, v201, v229, s27
	global_store_short_d16_hi v221, v229, s[48:49] offset:320
	v_bfe_u32 v230, v202, 16, 1
	v_add3_u32 v230, v202, v230, s27
	global_store_short_d16_hi v221, v230, s[48:49] offset:576
	v_bfe_u32 v231, v203, 16, 1
	v_add3_u32 v231, v203, v231, s27
	global_store_short_d16_hi v221, v231, s[48:49] offset:832
	v_bfe_u32 v228, v222, 16, 1
	v_add3_u32 v228, v222, v228, s27
	global_store_short_d16_hi v221, v228, s[48:49] offset:96
	v_bfe_u32 v229, v223, 16, 1
	v_add3_u32 v229, v223, v229, s27
	global_store_short_d16_hi v221, v229, s[48:49] offset:352
	v_bfe_u32 v230, v224, 16, 1
	v_add3_u32 v230, v224, v230, s27
	global_store_short_d16_hi v221, v230, s[48:49] offset:608
	v_bfe_u32 v231, v225, 16, 1
	v_add3_u32 v231, v225, v231, s27
	global_store_short_d16_hi v221, v231, s[48:49] offset:864
	s_add_u32 s48, s48, s6
	s_addc_u32 s49, s49, s92
	v_mul_f32_e32 v227, 0x3fb8aa3b, v232
	v_exp_f32_e32 v227, v227
	s_nop 0
	v_mul_f32_e32 v188, v188, v227
	v_mul_f32_e32 v189, v189, v227
	v_mul_f32_e32 v190, v190, v227
	v_mul_f32_e32 v191, v191, v227
	v_mul_f32_e32 v192, v192, v227
	v_mul_f32_e32 v193, v193, v227
	v_mul_f32_e32 v194, v194, v227
	v_mul_f32_e32 v195, v195, v227
	v_mul_f32_e32 v200, v200, v227
	v_mul_f32_e32 v201, v201, v227
	v_mul_f32_e32 v202, v202, v227
	v_mul_f32_e32 v203, v203, v227
	v_mul_f32_e32 v222, v222, v227
	v_mul_f32_e32 v223, v223, v227
	v_mul_f32_e32 v224, v224, v227
	v_mul_f32_e32 v225, v225, v227
	ds_read_b128 v[172:175], v233 offset:128
	ds_read_b128 v[176:179], v233 offset:144
	s_waitcnt lgkmcnt(2)
	v_lshlrev_b32_e32 v228, 16, v84
	v_and_b32_e32 v229, s28, v84
	v_mul_f32_e32 v228, v228, v164
	v_mul_f32_e32 v229, v229, v165
	v_cvt_pk_bf16_f32 v180, v228, v229
	v_lshlrev_b32_e32 v228, 16, v85
	v_and_b32_e32 v229, s28, v85
	v_mul_f32_e32 v228, v228, v166
	v_mul_f32_e32 v229, v229, v167
	v_cvt_pk_bf16_f32 v181, v228, v229
	v_lshlrev_b32_e32 v228, 16, v86
	v_and_b32_e32 v229, s28, v86
	v_mul_f32_e32 v228, v228, v168
	v_mul_f32_e32 v229, v229, v169
	v_cvt_pk_bf16_f32 v182, v228, v229
	v_lshlrev_b32_e32 v228, 16, v87
	v_and_b32_e32 v229, s28, v87
	v_mul_f32_e32 v228, v228, v170
	v_mul_f32_e32 v229, v229, v171
	v_cvt_pk_bf16_f32 v183, v228, v229
	s_nop 1
	v_mfma_f32_16x16x32_bf16 v[188:191], v[180:183], v[100:103], v[188:191]
	v_mfma_f32_16x16x32_bf16 v[192:195], v[180:183], v[104:107], v[192:195]
	v_mfma_f32_16x16x32_bf16 v[200:203], v[180:183], v[108:111], v[200:203]
	v_mfma_f32_16x16x32_bf16 v[222:225], v[180:183], v[112:115], v[222:225]
	ds_read_b128 v[164:167], v233 offset:256
	ds_read_b128 v[168:171], v233 offset:272
	s_waitcnt lgkmcnt(2)
	v_lshlrev_b32_e32 v228, 16, v88
	v_and_b32_e32 v229, s28, v88
	v_mul_f32_e32 v228, v228, v172
	v_mul_f32_e32 v229, v229, v173
	v_cvt_pk_bf16_f32 v184, v228, v229
	v_lshlrev_b32_e32 v228, 16, v89
	v_and_b32_e32 v229, s28, v89
	v_mul_f32_e32 v228, v228, v174
	v_mul_f32_e32 v229, v229, v175
	v_cvt_pk_bf16_f32 v185, v228, v229
	v_lshlrev_b32_e32 v228, 16, v90
	v_and_b32_e32 v229, s28, v90
	v_mul_f32_e32 v228, v228, v176
	v_mul_f32_e32 v229, v229, v177
	v_cvt_pk_bf16_f32 v186, v228, v229
	v_lshlrev_b32_e32 v228, 16, v91
	v_and_b32_e32 v229, s28, v91
	v_mul_f32_e32 v228, v228, v178
	v_mul_f32_e32 v229, v229, v179
	v_cvt_pk_bf16_f32 v187, v228, v229
	s_nop 1
	v_mfma_f32_16x16x32_bf16 v[188:191], v[184:187], v[116:119], v[188:191]
	v_mfma_f32_16x16x32_bf16 v[192:195], v[184:187], v[120:123], v[192:195]
	v_mfma_f32_16x16x32_bf16 v[200:203], v[184:187], v[124:127], v[200:203]
	v_mfma_f32_16x16x32_bf16 v[222:225], v[184:187], v[128:131], v[222:225]
	ds_read_b128 v[172:175], v233 offset:384
	ds_read_b128 v[176:179], v233 offset:400
	s_waitcnt lgkmcnt(2)
	v_lshlrev_b32_e32 v228, 16, v92
	v_and_b32_e32 v229, s28, v92
	v_mul_f32_e32 v228, v228, v164
	v_mul_f32_e32 v229, v229, v165
	v_cvt_pk_bf16_f32 v180, v228, v229
	v_lshlrev_b32_e32 v228, 16, v93
	v_and_b32_e32 v229, s28, v93
	v_mul_f32_e32 v228, v228, v166
	v_mul_f32_e32 v229, v229, v167
	v_cvt_pk_bf16_f32 v181, v228, v229
	v_lshlrev_b32_e32 v228, 16, v94
	v_and_b32_e32 v229, s28, v94
	v_mul_f32_e32 v228, v228, v168
	v_mul_f32_e32 v229, v229, v169
	v_cvt_pk_bf16_f32 v182, v228, v229
	v_lshlrev_b32_e32 v228, 16, v95
	v_and_b32_e32 v229, s28, v95
	v_mul_f32_e32 v228, v228, v170
	v_mul_f32_e32 v229, v229, v171
	v_cvt_pk_bf16_f32 v183, v228, v229
	s_nop 1
	v_mfma_f32_16x16x32_bf16 v[188:191], v[180:183], v[132:135], v[188:191]
	v_mfma_f32_16x16x32_bf16 v[192:195], v[180:183], v[136:139], v[192:195]
	v_mfma_f32_16x16x32_bf16 v[200:203], v[180:183], v[140:143], v[200:203]
	v_mfma_f32_16x16x32_bf16 v[222:225], v[180:183], v[144:147], v[222:225]
	s_waitcnt lgkmcnt(0)
	v_lshlrev_b32_e32 v228, 16, v96
	v_and_b32_e32 v229, s28, v96
	v_mul_f32_e32 v228, v228, v172
	v_mul_f32_e32 v229, v229, v173
	v_cvt_pk_bf16_f32 v184, v228, v229
	v_lshlrev_b32_e32 v228, 16, v97
	v_and_b32_e32 v229, s28, v97
	v_mul_f32_e32 v228, v228, v174
	v_mul_f32_e32 v229, v229, v175
	v_cvt_pk_bf16_f32 v185, v228, v229
	v_lshlrev_b32_e32 v228, 16, v98
	v_and_b32_e32 v229, s28, v98
	v_mul_f32_e32 v228, v228, v176
	v_mul_f32_e32 v229, v229, v177
	v_cvt_pk_bf16_f32 v186, v228, v229
	v_lshlrev_b32_e32 v228, 16, v99
	v_and_b32_e32 v229, s28, v99
	v_mul_f32_e32 v228, v228, v178
	v_mul_f32_e32 v229, v229, v179
	v_cvt_pk_bf16_f32 v187, v228, v229
	s_nop 1
	v_mfma_f32_16x16x32_bf16 v[188:191], v[184:187], v[148:151], v[188:191]
	v_mfma_f32_16x16x32_bf16 v[192:195], v[184:187], v[152:155], v[192:195]
	v_mfma_f32_16x16x32_bf16 v[200:203], v[184:187], v[156:159], v[200:203]
	v_mfma_f32_16x16x32_bf16 v[222:225], v[184:187], v[160:163], v[222:225]
	s_nop 7
	v_readlane_b32 s58, v237, 7
	v_readlane_b32 s59, v237, 8
	s_lshl_b32 s100, s8, 15
	s_lshl_b32 s9, s42, 13
	s_add_u32 s100, s100, s9
	s_lshl_b32 s9, s43, 6
	s_add_u32 s100, s100, s9
	s_add_u32 s100, s100, 0x1800000
	s_add_u32 s58, s58, s100
	s_addc_u32 s59, s59, 0
	s_nop 3
	global_store_dword v205, v188, s[58:59] offset:0
	global_store_dword v205, v189, s[58:59] offset:512
	global_store_dword v205, v190, s[58:59] offset:1024
	global_store_dword v205, v191, s[58:59] offset:1536
	global_store_dword v205, v192, s[58:59] offset:64
	global_store_dword v205, v193, s[58:59] offset:576
	global_store_dword v205, v194, s[58:59] offset:1088
	global_store_dword v205, v195, s[58:59] offset:1600
	global_store_dword v205, v200, s[58:59] offset:128
	global_store_dword v205, v201, s[58:59] offset:640
	global_store_dword v205, v202, s[58:59] offset:1152
	global_store_dword v205, v203, s[58:59] offset:1664
	global_store_dword v205, v222, s[58:59] offset:192
	global_store_dword v205, v223, s[58:59] offset:704
	global_store_dword v205, v224, s[58:59] offset:1216
	global_store_dword v205, v225, s[58:59] offset:1728
	s_branch .LBB0_632
